# RS-phase GEMM epilogues (P1,P4,P9,P12): vmcnt(0) at the row-scale join moved into the global-load path only; counted wait after the last store instead
# speedup vs baseline: 1.0030x; 1.0006x over previous
; #define LAS __attribute__((address_space(3)))
; __device__ __forceinline__ unsigned pk2(float lo, float hi) { bf16x2_t r = __builtin_convertvector((f32x2_t){lo, hi}, bf16x2_t); return __builtin_bit_cast(unsigned, r); }
; __device__ __forceinline__ float sigmoid_fast(float x) { return __builtin_amdgcn_rcpf(1.0f + __builtin_amdgcn_exp2f(-1.44269504089f * x)); }
; __device__ __forceinline__ void rs_rows(const LAS unsigned char* lds, const float* rs, int pm, int wr, int fr, float (&rv)[2][4]) {
;     const LAS int* keys = (const LAS int*)(lds + RS_KEY_OFF); const LAS float* tab = (const LAS float*)(lds + RS_TAB_OFF);
;     const int k0 = keys[0], k1 = keys[1], k2 = keys[2], k3 = keys[3];
;     const int idx = (pm == k0) ? 0 : (pm == k1) ? 1 : (pm == k2) ? 2 : (pm == k3) ? 3 : -1;
;     const int rl = wr * 64 + fr;
;     if (idx >= 0) {
; #pragma unroll
;         for (int ai = 0; ai < 2; ++ai)
; #pragma unroll
;             for (int m = 0; m < 4; ++m) rv[ai][m] = tab[idx * 256 + rl + ai * 128 + m * 16];
;     } else {
; #pragma unroll
;         for (int ai = 0; ai < 2; ++ai)
; #pragma unroll
;             for (int m = 0; m < 4; ++m) rv[ai][m] = rs[pm * 256 + rl + ai * 128 + m * 16];
;     }
; }
;     __device__ __forceinline__ void operator()(const pg8::f32x4 (&acc)[2][2][4][2], const pg8::Unit& u, int wr, int wc, int fr, int fq) const {
;     ...
;                 const float rv = rvs[ai][m];
;                 bf16* p = O + (size_t)(row0 + ai * 128 + m * 16) * FF + col0;
;                 const pg8::f32x4 g0 = acc[ai][0][m][0] * rv, g1 = acc[ai][0][m][1] * rv, u0 = acc[ai][1][m][0] * rv, u1 = acc[ai][1][m][1] * rv;
;                 float r[8];
; #pragma unroll
;                 for (int j = 0; j < 4; ++j) { r[j] = g0[j] * sigmoid_fast(g0[j]) * u0[j]; r[4 + j] = g1[j] * sigmoid_fast(g1[j]) * u1[j]; }
;                 v4u w; w.x = pk2(r[0], r[1]); w.y = pk2(r[2], r[3]); w.z = pk2(r[4], r[5]); w.w = pk2(r[6], r[7]);
;                 __builtin_nontemporal_store(w, (v4u*)p);
.LBB0_249:
	s_lshl_b32 s21, s36, 8
	v_cmp_lt_i32_e32 vcc, -1, v149
	s_mov_b64 s[36:37], -1
	s_and_b64 vcc, exec, vcc
	v_add_u32_e32 v150, s21, v145
	s_cbranch_vccnz .LBB0_251
	v_add_u32_e32 v146, s21, v145
	v_ashrrev_i32_e32 v147, 31, v146
	v_lshl_add_u64 v[164:165], v[146:147], 2, s[92:93]
	global_load_dword v162, v[164:165], off
	global_load_dword v160, v[164:165], off offset:64
	global_load_dword v158, v[164:165], off offset:128
	global_load_dword v156, v[164:165], off offset:192
	global_load_dword v154, v[164:165], off offset:512
	global_load_dword v152, v[164:165], off offset:576
	global_load_dword v148, v[164:165], off offset:640
	global_load_dword v144, v[164:165], off offset:704
	s_mov_b64 s[36:37], 0
	v_mov_b64_e32 v[164:165], v[146:147]
	s_waitcnt vmcnt(0)
.LBB0_251:
	s_andn2_b64 vcc, exec, s[36:37]
	s_cbranch_vccnz .LBB0_253
	v_lshl_add_u32 v144, v149, 10, v157
	ds_read2_b32 v[162:163], v144 offset1:16
	ds_read2_b32 v[158:159], v144 offset0:32 offset1:48
	ds_read2_b32 v[154:155], v144 offset0:128 offset1:144
	ds_read2_b32 v[148:149], v144 offset0:160 offset1:176
	v_ashrrev_i32_e32 v151, 31, v150
	v_mov_b64_e32 v[164:165], v[150:151]
	v_mov_b32_e32 v146, v150
	s_waitcnt lgkmcnt(1)
	v_mov_b32_e32 v152, v155
	v_mov_b32_e32 v156, v159
	v_mov_b32_e32 v160, v163
	s_waitcnt lgkmcnt(0)
	v_mov_b32_e32 v144, v149
.LBB0_253:
	v_pk_mul_f32 v[124:125], v[124:125], v[162:163] op_sel_hi:[1,0]
	v_mov_b64_e32 v[150:151], s[16:17]
	v_mul_f32_e32 v147, 0xbfb8aa3b, v124
	v_exp_f32_e32 v147, v147
	v_mul_f32_e32 v149, 0xbfb8aa3b, v125
	v_exp_f32_e32 v149, v149
	v_mad_u64_u32 v[172:173], s[36:37], v164, s63, v[150:151]
	v_mov_b32_e32 v164, v173
	v_mad_u64_u32 v[164:165], s[36:37], v165, s63, v[164:165]
	v_add_f32_e32 v147, 1.0, v147
	v_pk_mul_f32 v[120:121], v[120:121], v[162:163] op_sel_hi:[1,0]
	v_mov_b32_e32 v173, v164
	v_rcp_f32_e32 v164, v147
	v_add_f32_e32 v147, 1.0, v149
	v_mul_f32_e32 v149, 0xbfb8aa3b, v120
	v_exp_f32_e32 v149, v149
	v_mul_f32_e32 v155, 0xbfb8aa3b, v121
	v_rcp_f32_e32 v165, v147
	v_exp_f32_e32 v155, v155
	v_add_f32_e32 v147, 1.0, v149
	v_pk_mul_f32 v[116:117], v[116:117], v[162:163] op_sel_hi:[1,0]
	v_pk_mul_f32 v[124:125], v[124:125], v[164:165]
	v_rcp_f32_e32 v174, v147
	v_add_f32_e32 v147, 1.0, v155
	v_pk_mul_f32 v[116:117], v[116:117], v[124:125]
	v_pk_mul_f32 v[124:125], v[126:127], v[162:163] op_sel_hi:[1,0]
	v_rcp_f32_e32 v175, v147
	v_mul_f32_e32 v126, 0xbfb8aa3b, v124
	v_mul_f32_e32 v127, 0xbfb8aa3b, v125
	v_exp_f32_e32 v126, v126
	v_exp_f32_e32 v127, v127
	v_pk_mul_f32 v[120:121], v[120:121], v[174:175]
	v_pk_mul_f32 v[112:113], v[112:113], v[162:163] op_sel_hi:[1,0]
	v_pk_mul_f32 v[122:123], v[122:123], v[162:163] op_sel_hi:[1,0]
	v_pk_mul_f32 v[120:121], v[112:113], v[120:121]
	v_add_f32_e32 v112, 1.0, v126
	v_add_f32_e32 v113, 1.0, v127
	v_mul_f32_e32 v126, 0xbfb8aa3b, v122
	v_mul_f32_e32 v127, 0xbfb8aa3b, v123
	v_exp_f32_e32 v126, v126
	v_exp_f32_e32 v127, v127
	v_rcp_f32_e32 v112, v112
	v_rcp_f32_e32 v113, v113
	v_add_f32_e32 v126, 1.0, v126
	v_add_f32_e32 v127, 1.0, v127
	v_rcp_f32_e32 v126, v126
	v_rcp_f32_e32 v127, v127
	v_lshl_or_b32 v170, s66, 7, v161
	v_pk_mul_f32 v[112:113], v[124:125], v[112:113]
	v_pk_mul_f32 v[118:119], v[118:119], v[162:163] op_sel_hi:[1,0]
	v_ashrrev_i32_e32 v171, 31, v170
	v_pk_mul_f32 v[118:119], v[118:119], v[112:113]
	v_pk_mul_f32 v[112:113], v[122:123], v[126:127]
	v_pk_mul_f32 v[114:115], v[114:115], v[162:163] op_sel_hi:[1,0]
	v_pk_mul_f32 v[108:109], v[108:109], v[160:161] op_sel_hi:[1,0]
	v_pk_mul_f32 v[122:123], v[114:115], v[112:113]
	v_lshlrev_b64 v[112:113], 1, v[170:171]
	v_lshl_add_u64 v[124:125], v[172:173], 0, v[112:113]
	v_cvt_pk_bf16_f32 v114, v116, v117
	v_cvt_pk_bf16_f32 v115, v118, v119
	v_cvt_pk_bf16_f32 v116, v120, v121
	v_cvt_pk_bf16_f32 v117, v122, v123
	global_store_dwordx4 v[124:125], v[114:117], off nt
	v_pk_mul_f32 v[104:105], v[104:105], v[160:161] op_sel_hi:[1,0]
	v_pk_mul_f32 v[100:101], v[100:101], v[160:161] op_sel_hi:[1,0]
	v_mul_f32_e32 v115, 0xbfb8aa3b, v108
	v_exp_f32_e32 v116, v115
	v_mul_f32_e32 v115, 0xbfb8aa3b, v109
	v_exp_f32_e32 v117, v115
	v_mul_f32_e32 v118, 0xbfb8aa3b, v104
	v_add_f32_e32 v116, 1.0, v116
	v_rcp_f32_e32 v116, v116
	v_add_f32_e32 v117, 1.0, v117
	v_mul_f32_e32 v119, 0xbfb8aa3b, v105
	v_rcp_f32_e32 v117, v117
	v_exp_f32_e32 v118, v118
	v_exp_f32_e32 v119, v119
	v_pk_mul_f32 v[96:97], v[96:97], v[160:161] op_sel_hi:[1,0]
	v_pk_mul_f32 v[108:109], v[108:109], v[116:117]
	v_add_f32_e32 v118, 1.0, v118
	v_add_f32_e32 v119, 1.0, v119
	v_pk_mul_f32 v[100:101], v[100:101], v[108:109]
	v_pk_mul_f32 v[108:109], v[110:111], v[160:161] op_sel_hi:[1,0]
	v_rcp_f32_e32 v118, v118
	v_rcp_f32_e32 v119, v119
	v_mul_f32_e32 v110, 0xbfb8aa3b, v108
	v_mul_f32_e32 v111, 0xbfb8aa3b, v109
	v_exp_f32_e32 v110, v110
	v_exp_f32_e32 v111, v111
	v_pk_mul_f32 v[104:105], v[104:105], v[118:119]
	v_pk_mul_f32 v[106:107], v[106:107], v[160:161] op_sel_hi:[1,0]
	v_pk_mul_f32 v[104:105], v[96:97], v[104:105]
	v_add_f32_e32 v96, 1.0, v110
	v_add_f32_e32 v97, 1.0, v111
	v_mul_f32_e32 v110, 0xbfb8aa3b, v106
	v_mul_f32_e32 v111, 0xbfb8aa3b, v107
	v_exp_f32_e32 v110, v110
	v_exp_f32_e32 v111, v111
	v_rcp_f32_e32 v96, v96
	v_rcp_f32_e32 v97, v97
	v_add_f32_e32 v110, 1.0, v110
	v_add_f32_e32 v111, 1.0, v111
	v_rcp_f32_e32 v110, v110
	v_rcp_f32_e32 v111, v111
	v_pk_mul_f32 v[96:97], v[108:109], v[96:97]
	v_pk_mul_f32 v[102:103], v[102:103], v[160:161] op_sel_hi:[1,0]
	v_or_b32_e32 v114, 16, v146
	v_pk_mul_f32 v[102:103], v[102:103], v[96:97]
	v_pk_mul_f32 v[96:97], v[106:107], v[110:111]
	v_pk_mul_f32 v[98:99], v[98:99], v[160:161] op_sel_hi:[1,0]
; __device__ __forceinline__ unsigned pk2(float lo, float hi) { bf16x2_t r = __builtin_convertvector((f32x2_t){lo, hi}, bf16x2_t); return __builtin_bit_cast(unsigned, r); }
; __device__ __forceinline__ float sigmoid_fast(float x) { return __builtin_amdgcn_rcpf(1.0f + __builtin_amdgcn_exp2f(-1.44269504089f * x)); }
;     __device__ __forceinline__ void operator()(const pg8::f32x4 (&acc)[2][2][4][2], const pg8::Unit& u, int wr, int wc, int fr, int fq) const {
;     ...
;                 const float rv = rvs[ai][m];
;                 bf16* p = O + (size_t)(row0 + ai * 128 + m * 16) * FF + col0;
;                 const pg8::f32x4 g0 = acc[ai][0][m][0] * rv, g1 = acc[ai][0][m][1] * rv, u0 = acc[ai][1][m][0] * rv, u1 = acc[ai][1][m][1] * rv;
;                 float r[8];
; #pragma unroll
;                 for (int j = 0; j < 4; ++j) { r[j] = g0[j] * sigmoid_fast(g0[j]) * u0[j]; r[4 + j] = g1[j] * sigmoid_fast(g1[j]) * u1[j]; }
;                 v4u w; w.x = pk2(r[0], r[1]); w.y = pk2(r[2], r[3]); w.z = pk2(r[4], r[5]); w.w = pk2(r[6], r[7]);
;                 __builtin_nontemporal_store(w, (v4u*)p);
	v_mad_i64_i32 v[114:115], s[36:37], v114, s63, v[150:151]
	v_pk_mul_f32 v[106:107], v[98:99], v[96:97]
	v_lshl_add_u64 v[108:109], v[114:115], 0, v[112:113]
	v_cvt_pk_bf16_f32 v96, v100, v101
	v_cvt_pk_bf16_f32 v97, v102, v103
	v_cvt_pk_bf16_f32 v98, v104, v105
	v_cvt_pk_bf16_f32 v99, v106, v107
	v_pk_mul_f32 v[92:93], v[92:93], v[158:159] op_sel_hi:[1,0]
	global_store_dwordx4 v[108:109], v[96:99], off nt
	v_pk_mul_f32 v[88:89], v[88:89], v[158:159] op_sel_hi:[1,0]
	v_pk_mul_f32 v[84:85], v[84:85], v[158:159] op_sel_hi:[1,0]
	v_mul_f32_e32 v97, 0xbfb8aa3b, v92
	v_exp_f32_e32 v98, v97
	v_mul_f32_e32 v97, 0xbfb8aa3b, v93
	v_exp_f32_e32 v99, v97
	v_mul_f32_e32 v100, 0xbfb8aa3b, v88
	v_add_f32_e32 v98, 1.0, v98
	v_rcp_f32_e32 v98, v98
	v_add_f32_e32 v99, 1.0, v99
	v_mul_f32_e32 v101, 0xbfb8aa3b, v89
	v_rcp_f32_e32 v99, v99
	v_exp_f32_e32 v100, v100
	v_exp_f32_e32 v101, v101
	v_pk_mul_f32 v[80:81], v[80:81], v[158:159] op_sel_hi:[1,0]
	v_pk_mul_f32 v[92:93], v[92:93], v[98:99]
	v_add_f32_e32 v100, 1.0, v100
	v_add_f32_e32 v101, 1.0, v101
	v_pk_mul_f32 v[84:85], v[84:85], v[92:93]
	v_pk_mul_f32 v[92:93], v[94:95], v[158:159] op_sel_hi:[1,0]
	v_rcp_f32_e32 v100, v100
	v_rcp_f32_e32 v101, v101
	v_mul_f32_e32 v94, 0xbfb8aa3b, v92
	v_mul_f32_e32 v95, 0xbfb8aa3b, v93
	v_exp_f32_e32 v94, v94
	v_exp_f32_e32 v95, v95
	v_pk_mul_f32 v[88:89], v[88:89], v[100:101]
	v_pk_mul_f32 v[90:91], v[90:91], v[158:159] op_sel_hi:[1,0]
	v_pk_mul_f32 v[88:89], v[80:81], v[88:89]
	v_add_f32_e32 v80, 1.0, v94
	v_add_f32_e32 v81, 1.0, v95
	v_mul_f32_e32 v94, 0xbfb8aa3b, v90
	v_mul_f32_e32 v95, 0xbfb8aa3b, v91
	v_exp_f32_e32 v94, v94
	v_exp_f32_e32 v95, v95
	v_rcp_f32_e32 v80, v80
	v_rcp_f32_e32 v81, v81
	v_add_f32_e32 v94, 1.0, v94
	v_add_f32_e32 v95, 1.0, v95
	v_rcp_f32_e32 v94, v94
	v_rcp_f32_e32 v95, v95
	v_pk_mul_f32 v[80:81], v[92:93], v[80:81]
	v_pk_mul_f32 v[86:87], v[86:87], v[158:159] op_sel_hi:[1,0]
	v_or_b32_e32 v96, 32, v146
	v_pk_mul_f32 v[86:87], v[86:87], v[80:81]
	v_pk_mul_f32 v[80:81], v[90:91], v[94:95]
	v_pk_mul_f32 v[82:83], v[82:83], v[158:159] op_sel_hi:[1,0]
	v_mad_i64_i32 v[96:97], s[36:37], v96, s63, v[150:151]
	v_pk_mul_f32 v[90:91], v[82:83], v[80:81]
	v_lshl_add_u64 v[92:93], v[96:97], 0, v[112:113]
	v_cvt_pk_bf16_f32 v80, v84, v85
	v_cvt_pk_bf16_f32 v81, v86, v87
	v_cvt_pk_bf16_f32 v82, v88, v89
	v_cvt_pk_bf16_f32 v83, v90, v91
	v_pk_mul_f32 v[76:77], v[76:77], v[156:157] op_sel_hi:[1,0]
	global_store_dwordx4 v[92:93], v[80:83], off nt
	v_pk_mul_f32 v[72:73], v[72:73], v[156:157] op_sel_hi:[1,0]
	v_pk_mul_f32 v[68:69], v[68:69], v[156:157] op_sel_hi:[1,0]
	v_mul_f32_e32 v81, 0xbfb8aa3b, v76
	v_exp_f32_e32 v82, v81
	v_mul_f32_e32 v81, 0xbfb8aa3b, v77
	v_exp_f32_e32 v83, v81
	v_mul_f32_e32 v84, 0xbfb8aa3b, v72
	v_add_f32_e32 v82, 1.0, v82
	v_rcp_f32_e32 v82, v82
	v_add_f32_e32 v83, 1.0, v83
	v_mul_f32_e32 v85, 0xbfb8aa3b, v73
	v_rcp_f32_e32 v83, v83
	v_exp_f32_e32 v84, v84
	v_exp_f32_e32 v85, v85
	v_pk_mul_f32 v[64:65], v[64:65], v[156:157] op_sel_hi:[1,0]
	v_pk_mul_f32 v[76:77], v[76:77], v[82:83]
	v_add_f32_e32 v84, 1.0, v84
	v_add_f32_e32 v85, 1.0, v85
	v_pk_mul_f32 v[68:69], v[68:69], v[76:77]
	v_pk_mul_f32 v[76:77], v[78:79], v[156:157] op_sel_hi:[1,0]
	v_rcp_f32_e32 v84, v84
	v_rcp_f32_e32 v85, v85
	v_mul_f32_e32 v78, 0xbfb8aa3b, v76
	v_mul_f32_e32 v79, 0xbfb8aa3b, v77
	v_exp_f32_e32 v78, v78
	v_exp_f32_e32 v79, v79
	v_pk_mul_f32 v[72:73], v[72:73], v[84:85]
	v_pk_mul_f32 v[74:75], v[74:75], v[156:157] op_sel_hi:[1,0]
	v_pk_mul_f32 v[72:73], v[64:65], v[72:73]
	v_add_f32_e32 v64, 1.0, v78
	v_add_f32_e32 v65, 1.0, v79
	v_mul_f32_e32 v78, 0xbfb8aa3b, v74
	v_mul_f32_e32 v79, 0xbfb8aa3b, v75
	v_exp_f32_e32 v78, v78
	v_exp_f32_e32 v79, v79
	v_rcp_f32_e32 v64, v64
	v_rcp_f32_e32 v65, v65
	v_add_f32_e32 v78, 1.0, v78
	v_add_f32_e32 v79, 1.0, v79
	v_rcp_f32_e32 v78, v78
	v_rcp_f32_e32 v79, v79
	v_pk_mul_f32 v[64:65], v[76:77], v[64:65]
	v_pk_mul_f32 v[70:71], v[70:71], v[156:157] op_sel_hi:[1,0]
	v_or_b32_e32 v80, 48, v146
	v_pk_mul_f32 v[70:71], v[70:71], v[64:65]
	v_pk_mul_f32 v[64:65], v[74:75], v[78:79]
	v_pk_mul_f32 v[66:67], v[66:67], v[156:157] op_sel_hi:[1,0]
	v_mad_i64_i32 v[80:81], s[36:37], v80, s63, v[150:151]
	v_pk_mul_f32 v[74:75], v[66:67], v[64:65]
	v_lshl_add_u64 v[76:77], v[80:81], 0, v[112:113]
	v_cvt_pk_bf16_f32 v64, v68, v69
	v_cvt_pk_bf16_f32 v65, v70, v71
	v_cvt_pk_bf16_f32 v66, v72, v73
	v_cvt_pk_bf16_f32 v67, v74, v75
	v_pk_mul_f32 v[60:61], v[60:61], v[154:155] op_sel_hi:[1,0]
	global_store_dwordx4 v[76:77], v[64:67], off nt
	v_pk_mul_f32 v[56:57], v[56:57], v[154:155] op_sel_hi:[1,0]
	v_pk_mul_f32 v[52:53], v[52:53], v[154:155] op_sel_hi:[1,0]
	v_mul_f32_e32 v65, 0xbfb8aa3b, v60
	v_exp_f32_e32 v66, v65
	v_mul_f32_e32 v65, 0xbfb8aa3b, v61
	v_exp_f32_e32 v67, v65
	v_mul_f32_e32 v68, 0xbfb8aa3b, v56
	v_add_f32_e32 v66, 1.0, v66
	v_rcp_f32_e32 v66, v66
	v_add_f32_e32 v67, 1.0, v67
	v_mul_f32_e32 v69, 0xbfb8aa3b, v57
	v_rcp_f32_e32 v67, v67
	v_exp_f32_e32 v68, v68
	v_exp_f32_e32 v69, v69
	v_pk_mul_f32 v[48:49], v[48:49], v[154:155] op_sel_hi:[1,0]
	v_pk_mul_f32 v[60:61], v[60:61], v[66:67]
	v_add_f32_e32 v68, 1.0, v68
	v_add_f32_e32 v69, 1.0, v69
	v_pk_mul_f32 v[52:53], v[52:53], v[60:61]
	v_pk_mul_f32 v[60:61], v[62:63], v[154:155] op_sel_hi:[1,0]
	v_rcp_f32_e32 v68, v68
	v_rcp_f32_e32 v69, v69
	v_mul_f32_e32 v62, 0xbfb8aa3b, v60
	v_mul_f32_e32 v63, 0xbfb8aa3b, v61
	v_exp_f32_e32 v62, v62
	v_exp_f32_e32 v63, v63
	v_pk_mul_f32 v[56:57], v[56:57], v[68:69]
	v_pk_mul_f32 v[58:59], v[58:59], v[154:155] op_sel_hi:[1,0]
	v_pk_mul_f32 v[56:57], v[48:49], v[56:57]
	v_add_f32_e32 v48, 1.0, v62
	v_add_f32_e32 v49, 1.0, v63
; __device__ __forceinline__ unsigned pk2(float lo, float hi) { bf16x2_t r = __builtin_convertvector((f32x2_t){lo, hi}, bf16x2_t); return __builtin_bit_cast(unsigned, r); }
; __device__ __forceinline__ float sigmoid_fast(float x) { return __builtin_amdgcn_rcpf(1.0f + __builtin_amdgcn_exp2f(-1.44269504089f * x)); }
;     __device__ __forceinline__ void operator()(const pg8::f32x4 (&acc)[2][2][4][2], const pg8::Unit& u, int wr, int wc, int fr, int fq) const {
;     ...
;                 const float rv = rvs[ai][m];
;                 bf16* p = O + (size_t)(row0 + ai * 128 + m * 16) * FF + col0;
;                 const pg8::f32x4 g0 = acc[ai][0][m][0] * rv, g1 = acc[ai][0][m][1] * rv, u0 = acc[ai][1][m][0] * rv, u1 = acc[ai][1][m][1] * rv;
;                 float r[8];
; #pragma unroll
;                 for (int j = 0; j < 4; ++j) { r[j] = g0[j] * sigmoid_fast(g0[j]) * u0[j]; r[4 + j] = g1[j] * sigmoid_fast(g1[j]) * u1[j]; }
;                 v4u w; w.x = pk2(r[0], r[1]); w.y = pk2(r[2], r[3]); w.z = pk2(r[4], r[5]); w.w = pk2(r[6], r[7]);
;                 __builtin_nontemporal_store(w, (v4u*)p);
	v_mul_f32_e32 v62, 0xbfb8aa3b, v58
	v_mul_f32_e32 v63, 0xbfb8aa3b, v59
	v_exp_f32_e32 v62, v62
	v_exp_f32_e32 v63, v63
	v_rcp_f32_e32 v48, v48
	v_rcp_f32_e32 v49, v49
	v_add_f32_e32 v62, 1.0, v62
	v_add_f32_e32 v63, 1.0, v63
	v_rcp_f32_e32 v62, v62
	v_rcp_f32_e32 v63, v63
	v_pk_mul_f32 v[48:49], v[60:61], v[48:49]
	v_pk_mul_f32 v[54:55], v[54:55], v[154:155] op_sel_hi:[1,0]
	v_add_u32_e32 v64, 0x80, v146
	v_pk_mul_f32 v[54:55], v[54:55], v[48:49]
	v_pk_mul_f32 v[48:49], v[58:59], v[62:63]
	v_pk_mul_f32 v[50:51], v[50:51], v[154:155] op_sel_hi:[1,0]
	v_mad_i64_i32 v[64:65], s[36:37], v64, s63, v[150:151]
	v_pk_mul_f32 v[58:59], v[50:51], v[48:49]
	v_lshl_add_u64 v[60:61], v[64:65], 0, v[112:113]
	v_cvt_pk_bf16_f32 v48, v52, v53
	v_cvt_pk_bf16_f32 v49, v54, v55
	v_cvt_pk_bf16_f32 v50, v56, v57
	v_cvt_pk_bf16_f32 v51, v58, v59
	v_pk_mul_f32 v[44:45], v[44:45], v[152:153] op_sel_hi:[1,0]
	global_store_dwordx4 v[60:61], v[48:51], off nt
	v_pk_mul_f32 v[40:41], v[40:41], v[152:153] op_sel_hi:[1,0]
	v_pk_mul_f32 v[36:37], v[36:37], v[152:153] op_sel_hi:[1,0]
	v_mul_f32_e32 v49, 0xbfb8aa3b, v44
	v_exp_f32_e32 v50, v49
	v_mul_f32_e32 v49, 0xbfb8aa3b, v45
	v_exp_f32_e32 v51, v49
	v_mul_f32_e32 v52, 0xbfb8aa3b, v40
	v_add_f32_e32 v50, 1.0, v50
	v_rcp_f32_e32 v50, v50
	v_add_f32_e32 v51, 1.0, v51
	v_mul_f32_e32 v53, 0xbfb8aa3b, v41
	v_rcp_f32_e32 v51, v51
	v_exp_f32_e32 v52, v52
	v_exp_f32_e32 v53, v53
	v_pk_mul_f32 v[32:33], v[32:33], v[152:153] op_sel_hi:[1,0]
	v_pk_mul_f32 v[44:45], v[44:45], v[50:51]
	v_add_f32_e32 v52, 1.0, v52
	v_add_f32_e32 v53, 1.0, v53
	v_pk_mul_f32 v[36:37], v[36:37], v[44:45]
	v_pk_mul_f32 v[44:45], v[46:47], v[152:153] op_sel_hi:[1,0]
	v_rcp_f32_e32 v52, v52
	v_rcp_f32_e32 v53, v53
	v_mul_f32_e32 v46, 0xbfb8aa3b, v44
	v_mul_f32_e32 v47, 0xbfb8aa3b, v45
	v_exp_f32_e32 v46, v46
	v_exp_f32_e32 v47, v47
	v_pk_mul_f32 v[40:41], v[40:41], v[52:53]
	v_pk_mul_f32 v[42:43], v[42:43], v[152:153] op_sel_hi:[1,0]
	v_pk_mul_f32 v[40:41], v[32:33], v[40:41]
	v_add_f32_e32 v32, 1.0, v46
	v_add_f32_e32 v33, 1.0, v47
	v_mul_f32_e32 v46, 0xbfb8aa3b, v42
	v_mul_f32_e32 v47, 0xbfb8aa3b, v43
	v_exp_f32_e32 v46, v46
	v_exp_f32_e32 v47, v47
	v_rcp_f32_e32 v32, v32
	v_rcp_f32_e32 v33, v33
	v_add_f32_e32 v46, 1.0, v46
	v_add_f32_e32 v47, 1.0, v47
	v_rcp_f32_e32 v46, v46
	v_rcp_f32_e32 v47, v47
	v_pk_mul_f32 v[32:33], v[44:45], v[32:33]
	v_pk_mul_f32 v[38:39], v[38:39], v[152:153] op_sel_hi:[1,0]
	v_add_u32_e32 v48, 0x90, v146
	v_pk_mul_f32 v[38:39], v[38:39], v[32:33]
	v_pk_mul_f32 v[32:33], v[42:43], v[46:47]
	v_pk_mul_f32 v[34:35], v[34:35], v[152:153] op_sel_hi:[1,0]
	v_mad_i64_i32 v[48:49], s[36:37], v48, s63, v[150:151]
	v_pk_mul_f32 v[42:43], v[34:35], v[32:33]
	v_lshl_add_u64 v[44:45], v[48:49], 0, v[112:113]
	v_cvt_pk_bf16_f32 v32, v36, v37
	v_cvt_pk_bf16_f32 v33, v38, v39
	v_cvt_pk_bf16_f32 v34, v40, v41
	v_cvt_pk_bf16_f32 v35, v42, v43
	v_pk_mul_f32 v[28:29], v[28:29], v[148:149] op_sel_hi:[1,0]
	global_store_dwordx4 v[44:45], v[32:35], off nt
	v_pk_mul_f32 v[24:25], v[24:25], v[148:149] op_sel_hi:[1,0]
	v_pk_mul_f32 v[20:21], v[20:21], v[148:149] op_sel_hi:[1,0]
	v_mul_f32_e32 v33, 0xbfb8aa3b, v28
	v_exp_f32_e32 v34, v33
	v_mul_f32_e32 v33, 0xbfb8aa3b, v29
	v_exp_f32_e32 v35, v33
	v_mul_f32_e32 v36, 0xbfb8aa3b, v24
	v_add_f32_e32 v34, 1.0, v34
	v_rcp_f32_e32 v34, v34
	v_add_f32_e32 v35, 1.0, v35
	v_mul_f32_e32 v37, 0xbfb8aa3b, v25
	v_rcp_f32_e32 v35, v35
	v_exp_f32_e32 v36, v36
	v_exp_f32_e32 v37, v37
	v_pk_mul_f32 v[16:17], v[16:17], v[148:149] op_sel_hi:[1,0]
	v_pk_mul_f32 v[28:29], v[28:29], v[34:35]
; #define PG8_WAIT_V(n) asm volatile("s_waitcnt vmcnt(" #n ")" ::: "memory")
; #define PG8_BAR __builtin_amdgcn_s_barrier()
; __device__ __forceinline__ unsigned pk2(float lo, float hi) { bf16x2_t r = __builtin_convertvector((f32x2_t){lo, hi}, bf16x2_t); return __builtin_bit_cast(unsigned, r); }
; __device__ __forceinline__ float sigmoid_fast(float x) { return __builtin_amdgcn_rcpf(1.0f + __builtin_amdgcn_exp2f(-1.44269504089f * x)); }
;     ...
;         if constexpr (!Epi::AFTER_DRAIN) { E(acc, cur, wr, wc, fr, fq); S.done(cur); }
;         if (!has_next) break;
;         if constexpr (PEEL) { PG8_WAIT_V(8); }
; #pragma unroll
;         for (int a = 0; a < 2; ++a)
; #pragma unroll
;             for (int b = 0; b < 2; ++b)
; #pragma unroll
;                 for (int m = 0; m < 4; ++m)
; #pragma unroll
;                     for (int n = 0; n < 2; ++n) acc[a][b][m][n] = (f32x4){0.f, 0.f, 0.f, 0.f};
;         cur = nxt; cA = nA; cB = nB; ck = nk; ++ui;
;         if constexpr (ALIGN_EPI) { if (wr == 1) PG8_BAR; }
;     __device__ __forceinline__ void operator()(const pg8::f32x4 (&acc)[2][2][4][2], const pg8::Unit& u, int wr, int wc, int fr, int fq) const {
;     ...
;                 const float rv = rvs[ai][m];
;                 bf16* p = O + (size_t)(row0 + ai * 128 + m * 16) * FF + col0;
;                 const pg8::f32x4 g0 = acc[ai][0][m][0] * rv, g1 = acc[ai][0][m][1] * rv, u0 = acc[ai][1][m][0] * rv, u1 = acc[ai][1][m][1] * rv;
;                 float r[8];
; #pragma unroll
;                 for (int j = 0; j < 4; ++j) { r[j] = g0[j] * sigmoid_fast(g0[j]) * u0[j]; r[4 + j] = g1[j] * sigmoid_fast(g1[j]) * u1[j]; }
;                 v4u w; w.x = pk2(r[0], r[1]); w.y = pk2(r[2], r[3]); w.z = pk2(r[4], r[5]); w.w = pk2(r[6], r[7]);
;                 __builtin_nontemporal_store(w, (v4u*)p);
	v_add_f32_e32 v36, 1.0, v36
	v_add_f32_e32 v37, 1.0, v37
	v_pk_mul_f32 v[20:21], v[20:21], v[28:29]
	v_pk_mul_f32 v[28:29], v[30:31], v[148:149] op_sel_hi:[1,0]
	v_rcp_f32_e32 v36, v36
	v_rcp_f32_e32 v37, v37
	v_mul_f32_e32 v30, 0xbfb8aa3b, v28
	v_mul_f32_e32 v31, 0xbfb8aa3b, v29
	v_exp_f32_e32 v30, v30
	v_exp_f32_e32 v31, v31
	v_pk_mul_f32 v[24:25], v[24:25], v[36:37]
	v_pk_mul_f32 v[26:27], v[26:27], v[148:149] op_sel_hi:[1,0]
	v_pk_mul_f32 v[24:25], v[16:17], v[24:25]
	v_add_f32_e32 v16, 1.0, v30
	v_add_f32_e32 v17, 1.0, v31
	v_mul_f32_e32 v30, 0xbfb8aa3b, v26
	v_mul_f32_e32 v31, 0xbfb8aa3b, v27
	v_exp_f32_e32 v30, v30
	v_exp_f32_e32 v31, v31
	v_rcp_f32_e32 v16, v16
	v_rcp_f32_e32 v17, v17
	v_add_f32_e32 v30, 1.0, v30
	v_add_f32_e32 v31, 1.0, v31
	v_rcp_f32_e32 v30, v30
	v_rcp_f32_e32 v31, v31
	v_pk_mul_f32 v[16:17], v[28:29], v[16:17]
	v_pk_mul_f32 v[22:23], v[22:23], v[148:149] op_sel_hi:[1,0]
	v_add_u32_e32 v32, 0xa0, v146
	v_pk_mul_f32 v[22:23], v[22:23], v[16:17]
	v_pk_mul_f32 v[16:17], v[26:27], v[30:31]
	v_pk_mul_f32 v[18:19], v[18:19], v[148:149] op_sel_hi:[1,0]
	v_mad_i64_i32 v[32:33], s[36:37], v32, s63, v[150:151]
	v_pk_mul_f32 v[26:27], v[18:19], v[16:17]
	v_lshl_add_u64 v[28:29], v[32:33], 0, v[112:113]
	v_cvt_pk_bf16_f32 v16, v20, v21
	v_cvt_pk_bf16_f32 v17, v22, v23
	v_cvt_pk_bf16_f32 v18, v24, v25
	v_cvt_pk_bf16_f32 v19, v26, v27
	v_pk_mul_f32 v[12:13], v[12:13], v[144:145] op_sel_hi:[1,0]
	global_store_dwordx4 v[28:29], v[16:19], off nt
	v_pk_mul_f32 v[8:9], v[8:9], v[144:145] op_sel_hi:[1,0]
	v_pk_mul_f32 v[4:5], v[4:5], v[144:145] op_sel_hi:[1,0]
	v_mul_f32_e32 v17, 0xbfb8aa3b, v12
	v_exp_f32_e32 v18, v17
	v_mul_f32_e32 v17, 0xbfb8aa3b, v13
	v_exp_f32_e32 v19, v17
	v_mul_f32_e32 v20, 0xbfb8aa3b, v8
	v_add_f32_e32 v18, 1.0, v18
	v_rcp_f32_e32 v18, v18
	v_add_f32_e32 v19, 1.0, v19
	v_mul_f32_e32 v21, 0xbfb8aa3b, v9
	v_rcp_f32_e32 v19, v19
	v_exp_f32_e32 v20, v20
	v_exp_f32_e32 v21, v21
	v_pk_mul_f32 v[0:1], v[0:1], v[144:145] op_sel_hi:[1,0]
	v_pk_mul_f32 v[12:13], v[12:13], v[18:19]
	v_add_f32_e32 v20, 1.0, v20
	v_add_f32_e32 v21, 1.0, v21
	v_pk_mul_f32 v[4:5], v[4:5], v[12:13]
	v_pk_mul_f32 v[12:13], v[14:15], v[144:145] op_sel_hi:[1,0]
	v_rcp_f32_e32 v20, v20
	v_rcp_f32_e32 v21, v21
	v_mul_f32_e32 v14, 0xbfb8aa3b, v12
	v_mul_f32_e32 v15, 0xbfb8aa3b, v13
	v_exp_f32_e32 v14, v14
	v_exp_f32_e32 v15, v15
	v_pk_mul_f32 v[8:9], v[8:9], v[20:21]
	v_pk_mul_f32 v[10:11], v[10:11], v[144:145] op_sel_hi:[1,0]
	v_pk_mul_f32 v[8:9], v[0:1], v[8:9]
	v_add_f32_e32 v0, 1.0, v14
	v_add_f32_e32 v1, 1.0, v15
	v_mul_f32_e32 v14, 0xbfb8aa3b, v10
	v_mul_f32_e32 v15, 0xbfb8aa3b, v11
	v_exp_f32_e32 v14, v14
	v_exp_f32_e32 v15, v15
	v_rcp_f32_e32 v0, v0
	v_rcp_f32_e32 v1, v1
	v_add_f32_e32 v14, 1.0, v14
	v_add_f32_e32 v15, 1.0, v15
	v_rcp_f32_e32 v14, v14
	v_rcp_f32_e32 v15, v15
	v_pk_mul_f32 v[0:1], v[12:13], v[0:1]
	v_pk_mul_f32 v[6:7], v[6:7], v[144:145] op_sel_hi:[1,0]
	v_add_u32_e32 v16, 0xb0, v146
	v_pk_mul_f32 v[6:7], v[6:7], v[0:1]
	v_pk_mul_f32 v[0:1], v[10:11], v[14:15]
	v_pk_mul_f32 v[2:3], v[2:3], v[144:145] op_sel_hi:[1,0]
	v_mad_i64_i32 v[16:17], s[36:37], v16, s63, v[150:151]
	v_pk_mul_f32 v[10:11], v[2:3], v[0:1]
	v_lshl_add_u64 v[12:13], v[16:17], 0, v[112:113]
	v_cvt_pk_bf16_f32 v0, v4, v5
	v_cvt_pk_bf16_f32 v1, v6, v7
	v_cvt_pk_bf16_f32 v2, v8, v9
	v_cvt_pk_bf16_f32 v3, v10, v11
	s_andn2_b64 vcc, exec, s[0:1]
	s_mov_b64 s[0:1], -1
	global_store_dwordx4 v[12:13], v[0:3], off nt
	s_waitcnt vmcnt(8)
	s_cbranch_vccnz .LBB0_240
	s_andn2_b64 vcc, exec, s[4:5]
	s_cbranch_vccnz .LBB0_239
	s_barrier
	s_branch .LBB0_239

; #define LAS __attribute__((address_space(3)))
; __device__ __forceinline__ float sigmoid_fast(float x) { return __builtin_amdgcn_rcpf(1.0f + __builtin_amdgcn_exp2f(-1.44269504089f * x)); }
; __device__ __forceinline__ float gelu_tanh(float x) { return x * sigmoid_fast(1.5957691216f * (x + 0.044715f * x * x * x)); }
; __device__ __forceinline__ void rs_rows(const LAS unsigned char* lds, const float* rs, int pm, int wr, int fr, float (&rv)[2][4]) {
;     const LAS int* keys = (const LAS int*)(lds + RS_KEY_OFF); const LAS float* tab = (const LAS float*)(lds + RS_TAB_OFF);
;     const int k0 = keys[0], k1 = keys[1], k2 = keys[2], k3 = keys[3];
;     const int idx = (pm == k0) ? 0 : (pm == k1) ? 1 : (pm == k2) ? 2 : (pm == k3) ? 3 : -1;
;     const int rl = wr * 64 + fr;
;     if (idx >= 0) {
; #pragma unroll
;         for (int ai = 0; ai < 2; ++ai)
; #pragma unroll
;             for (int m = 0; m < 4; ++m) rv[ai][m] = tab[idx * 256 + rl + ai * 128 + m * 16];
;     } else {
; #pragma unroll
;         for (int ai = 0; ai < 2; ++ai)
; #pragma unroll
;             for (int m = 0; m < 4; ++m) rv[ai][m] = rs[pm * 256 + rl + ai * 128 + m * 16];
;     }
; }
;     __device__ __forceinline__ void operator()(const pg8::f32x4 (&acc)[2][2][4][2], const pg8::Unit& u, int wr, int wc, int fr, int fq) const {
;         float rvs[2][4]; rs_rows(lds, rs, u.pm, wr, fr, rvs);
;         const int t = u.pn >> 2;
;         bf16* O = base + (size_t)t * (SLAB / 2);
;         const int row0 = u.pm * 256 + wr * 64 + fr, col0 = (u.pn & 3) * 256 + wc * 32 + 8 * fq;
; #pragma unroll
;         for (int ai = 0; ai < 2; ++ai)
; #pragma unroll
;             for (int m = 0; m < 4; ++m) {
;                 const size_t off = (size_t)(row0 + ai * 128 + m * 16) * D + col0;
;                 const float rv = rvs[ai][m];
; #pragma unroll
;                 for (int bj = 0; bj < 2; ++bj) {
;                     float r[8];
; #pragma unroll
;                     for (int j = 0; j < 4; ++j) { r[j] = acc[ai][bj][m][0][j] * rv; r[4 + j] = acc[ai][bj][m][1][j] * rv; }
;                     if (t < 2) {
; #pragma unroll
;                         for (int j = 0; j < 8; ++j) r[j] = gelu_tanh(r[j]);
;                     } else if (t > 2) {
; #pragma unroll
;                         for (int j = 0; j < 8; ++j) r[j] = sigmoid_fast(r[j]);
;                     }
.LBB0_521:
	v_cmp_lt_i32_e32 vcc, -1, v136
	s_mov_b64 s[48:49], -1
	s_and_b64 vcc, exec, vcc
	v_lshl_add_u32 v166, s4, 8, v174
	s_cbranch_vccnz .LBB0_523
	v_lshl_add_u32 v148, s4, 8, v174
	v_ashrrev_i32_e32 v149, 31, v148
	v_lshl_add_u64 v[146:147], v[148:149], 2, s[92:93]
	global_load_dword v162, v[146:147], off
	global_load_dword v160, v[146:147], off offset:64
	global_load_dword v158, v[146:147], off offset:128
	global_load_dword v156, v[146:147], off offset:192
	global_load_dword v154, v[146:147], off offset:512
	global_load_dword v152, v[146:147], off offset:576
	global_load_dword v150, v[146:147], off offset:640
	s_nop 0
	global_load_dword v146, v[146:147], off offset:704
	s_mov_b64 s[48:49], 0
	v_mov_b64_e32 v[164:165], v[148:149]
	s_waitcnt vmcnt(0)
.LBB0_523:
	s_andn2_b64 vcc, exec, s[48:49]
	s_cbranch_vccnz .LBB0_525
	v_lshl_add_u32 v136, v136, 10, v176
	ds_read2_b32 v[162:163], v136 offset1:16
	ds_read2_b32 v[158:159], v136 offset0:32 offset1:48
	ds_read2_b32 v[154:155], v136 offset0:128 offset1:144
	ds_read2_b32 v[150:151], v136 offset0:160 offset1:176
	v_ashrrev_i32_e32 v167, 31, v166
	v_mov_b64_e32 v[164:165], v[166:167]
	v_mov_b32_e32 v148, v166
	s_waitcnt lgkmcnt(1)
	v_mov_b32_e32 v152, v155
	v_mov_b32_e32 v156, v159
	v_mov_b32_e32 v160, v163
	s_waitcnt lgkmcnt(0)
	v_mov_b32_e32 v146, v151
.LBB0_525:
	s_ashr_i32 s50, s6, 2
	s_cmp_gt_i32 s50, 1
	s_cselect_b64 s[48:49], -1, 0
	s_cmp_lg_u32 s50, 2
	s_cselect_b64 s[4:5], -1, 0
	v_cndmask_b32_e64 v136, 0, 1, s[4:5]
	v_pk_mul_f32 v[124:125], v[124:125], v[162:163] op_sel_hi:[1,0]
	v_pk_mul_f32 v[120:121], v[120:121], v[162:163] op_sel_hi:[1,0]
	v_pk_mul_f32 v[126:127], v[126:127], v[162:163] op_sel_hi:[1,0]
	v_pk_mul_f32 v[122:123], v[122:123], v[162:163] op_sel_hi:[1,0]
	s_mov_b64 s[52:53], -1
	s_and_b64 vcc, exec, s[48:49]
	v_cmp_ne_u32_e64 s[4:5], 1, v136
	s_cbranch_vccz .LBB0_528
	s_and_b64 vcc, exec, s[4:5]
	s_cbranch_vccnz .LBB0_608
	v_mul_f32_e32 v136, 0xbfb8aa3b, v124
	v_exp_f32_e32 v136, v136
	v_mul_f32_e32 v147, 0xbfb8aa3b, v125
	v_exp_f32_e32 v147, v147
	v_mul_f32_e32 v149, 0xbfb8aa3b, v127
	v_add_f32_e32 v136, 1.0, v136
	v_rcp_f32_e32 v166, v136
	v_mul_f32_e32 v136, 0xbfb8aa3b, v126
	v_exp_f32_e32 v136, v136
	v_exp_f32_e32 v149, v149
	v_add_f32_e32 v147, 1.0, v147
	v_rcp_f32_e32 v167, v147
	v_add_f32_e32 v136, 1.0, v136
	v_mul_f32_e32 v147, 0xbfb8aa3b, v120
	v_rcp_f32_e32 v168, v136
	v_add_f32_e32 v136, 1.0, v149
	v_exp_f32_e32 v147, v147
	v_mul_f32_e32 v149, 0xbfb8aa3b, v121
	v_exp_f32_e32 v149, v149
	v_rcp_f32_e32 v169, v136
	v_add_f32_e32 v136, 1.0, v147
	v_mul_f32_e32 v147, 0xbfb8aa3b, v122
	v_rcp_f32_e32 v170, v136
	v_add_f32_e32 v136, 1.0, v149
	v_exp_f32_e32 v147, v147
	v_mul_f32_e32 v149, 0xbfb8aa3b, v123
	v_exp_f32_e32 v149, v149
	v_rcp_f32_e32 v171, v136
	v_add_f32_e32 v136, 1.0, v147
	v_rcp_f32_e32 v172, v136
	v_add_f32_e32 v136, 1.0, v149
	v_rcp_f32_e32 v173, v136
	s_mov_b64 s[52:53], 0

; __device__ __forceinline__ unsigned pk2(float lo, float hi) { bf16x2_t r = __builtin_convertvector((f32x2_t){lo, hi}, bf16x2_t); return __builtin_bit_cast(unsigned, r); }
;     __device__ __forceinline__ void operator()(const pg8::f32x4 (&acc)[2][2][4][2], const pg8::Unit& u, int wr, int wc, int fr, int fq) const {
;     ...
;                     v4u w; w.x = pk2(r[0], r[1]); w.y = pk2(r[2], r[3]); w.z = pk2(r[4], r[5]); w.w = pk2(r[6], r[7]);
;                     __builtin_nontemporal_store(w, (v4u*)(O + off + bj * 128));
;                 }
.LBB0_605:
	s_mov_b64 s[4:5], 0x58000
	v_lshl_add_u64 v[4:5], v[8:9], 0, s[4:5]
	v_cvt_pk_bf16_f32 v0, v10, v11
	v_cvt_pk_bf16_f32 v1, v12, v13
	v_cvt_pk_bf16_f32 v2, v14, v15
	v_cvt_pk_bf16_f32 v3, v16, v17
	s_andn2_b64 vcc, exec, s[0:1]
	s_mov_b64 s[0:1], -1
	global_store_dwordx4 v[4:5], v[0:3], off offset:256 nt
	s_waitcnt vmcnt(16)
	s_cbranch_vccnz .LBB0_512
	s_andn2_b64 vcc, exec, s[14:15]
	s_cbranch_vccnz .LBB0_511
	s_barrier
	s_branch .LBB0_511

; #define LAS __attribute__((address_space(3)))
; __device__ __forceinline__ unsigned pk2(float lo, float hi) { bf16x2_t r = __builtin_convertvector((f32x2_t){lo, hi}, bf16x2_t); return __builtin_bit_cast(unsigned, r); }
; __device__ __forceinline__ float sigmoid_fast(float x) { return __builtin_amdgcn_rcpf(1.0f + __builtin_amdgcn_exp2f(-1.44269504089f * x)); }
; __device__ __forceinline__ void rs_rows(const LAS unsigned char* lds, const float* rs, int pm, int wr, int fr, float (&rv)[2][4]) {
;     const LAS int* keys = (const LAS int*)(lds + RS_KEY_OFF); const LAS float* tab = (const LAS float*)(lds + RS_TAB_OFF);
;     const int k0 = keys[0], k1 = keys[1], k2 = keys[2], k3 = keys[3];
;     const int idx = (pm == k0) ? 0 : (pm == k1) ? 1 : (pm == k2) ? 2 : (pm == k3) ? 3 : -1;
;     const int rl = wr * 64 + fr;
;     if (idx >= 0) {
; #pragma unroll
;         for (int ai = 0; ai < 2; ++ai)
; #pragma unroll
;             for (int m = 0; m < 4; ++m) rv[ai][m] = tab[idx * 256 + rl + ai * 128 + m * 16];
;     } else {
; #pragma unroll
;         for (int ai = 0; ai < 2; ++ai)
; #pragma unroll
;             for (int m = 0; m < 4; ++m) rv[ai][m] = rs[pm * 256 + rl + ai * 128 + m * 16];
;     }
; }
;     __device__ __forceinline__ void operator()(const pg8::f32x4 (&acc)[2][2][4][2], const pg8::Unit& u, int wr, int wc, int fr, int fq) const {
;     ...
;                 const float rv = rvs[ai][m];
;                 bf16* p = O + (size_t)(row0 + ai * 128 + m * 16) * FF + col0;
;                 const pg8::f32x4 g0 = acc[ai][0][m][0] * rv, g1 = acc[ai][0][m][1] * rv, u0 = acc[ai][1][m][0] * rv, u1 = acc[ai][1][m][1] * rv;
;                 float r[8];
; #pragma unroll
;                 for (int j = 0; j < 4; ++j) { r[j] = g0[j] * sigmoid_fast(g0[j]) * u0[j]; r[4 + j] = g1[j] * sigmoid_fast(g1[j]) * u1[j]; }
;                 v4u w; w.x = pk2(r[0], r[1]); w.y = pk2(r[2], r[3]); w.z = pk2(r[4], r[5]); w.w = pk2(r[6], r[7]);
;                 __builtin_nontemporal_store(w, (v4u*)p);
.LBB0_1076:
	s_lshl_b32 s13, s26, 8
	v_cmp_lt_i32_e32 vcc, -1, v149
	s_mov_b64 s[26:27], -1
	s_and_b64 vcc, exec, vcc
	v_add_u32_e32 v150, s13, v145
	s_cbranch_vccnz .LBB0_1078
	v_add_u32_e32 v146, s13, v145
	v_ashrrev_i32_e32 v147, 31, v146
	v_lshl_add_u64 v[164:165], v[146:147], 2, s[92:93]
	global_load_dword v162, v[164:165], off
	global_load_dword v160, v[164:165], off offset:64
	global_load_dword v158, v[164:165], off offset:128
	global_load_dword v156, v[164:165], off offset:192
	global_load_dword v154, v[164:165], off offset:512
	global_load_dword v152, v[164:165], off offset:576
	global_load_dword v148, v[164:165], off offset:640
	global_load_dword v144, v[164:165], off offset:704
	s_mov_b64 s[26:27], 0
	v_mov_b64_e32 v[164:165], v[146:147]
	s_waitcnt vmcnt(0)
.LBB0_1078:
	s_andn2_b64 vcc, exec, s[26:27]
	s_cbranch_vccnz .LBB0_1080
	v_lshl_add_u32 v144, v149, 10, v157
	ds_read2_b32 v[162:163], v144 offset1:16
	ds_read2_b32 v[158:159], v144 offset0:32 offset1:48
	ds_read2_b32 v[154:155], v144 offset0:128 offset1:144
	ds_read2_b32 v[148:149], v144 offset0:160 offset1:176
	v_ashrrev_i32_e32 v151, 31, v150
	v_mov_b64_e32 v[164:165], v[150:151]
	v_mov_b32_e32 v146, v150
	s_waitcnt lgkmcnt(1)
	v_mov_b32_e32 v152, v155
	v_mov_b32_e32 v156, v159
	v_mov_b32_e32 v160, v163
	s_waitcnt lgkmcnt(0)
	v_mov_b32_e32 v144, v149
.LBB0_1080:
	v_pk_mul_f32 v[124:125], v[124:125], v[162:163] op_sel_hi:[1,0]
	v_mov_b64_e32 v[150:151], s[16:17]
	v_mul_f32_e32 v147, 0xbfb8aa3b, v124
	v_exp_f32_e32 v147, v147
	v_mul_f32_e32 v149, 0xbfb8aa3b, v125
	v_exp_f32_e32 v149, v149
	v_mad_u64_u32 v[172:173], s[26:27], v164, s57, v[150:151]
	v_mov_b32_e32 v164, v173
	v_mad_u64_u32 v[164:165], s[26:27], v165, s57, v[164:165]
	v_add_f32_e32 v147, 1.0, v147
	v_pk_mul_f32 v[120:121], v[120:121], v[162:163] op_sel_hi:[1,0]
	v_mov_b32_e32 v173, v164
	v_rcp_f32_e32 v164, v147
	v_add_f32_e32 v147, 1.0, v149
	v_mul_f32_e32 v149, 0xbfb8aa3b, v120
	v_exp_f32_e32 v149, v149
	v_mul_f32_e32 v155, 0xbfb8aa3b, v121
	v_rcp_f32_e32 v165, v147
	v_exp_f32_e32 v155, v155
	v_add_f32_e32 v147, 1.0, v149
	v_pk_mul_f32 v[116:117], v[116:117], v[162:163] op_sel_hi:[1,0]
	v_pk_mul_f32 v[124:125], v[124:125], v[164:165]
	v_rcp_f32_e32 v174, v147
	v_add_f32_e32 v147, 1.0, v155
	v_pk_mul_f32 v[116:117], v[116:117], v[124:125]
	v_pk_mul_f32 v[124:125], v[126:127], v[162:163] op_sel_hi:[1,0]
	v_rcp_f32_e32 v175, v147
	v_mul_f32_e32 v126, 0xbfb8aa3b, v124
	v_mul_f32_e32 v127, 0xbfb8aa3b, v125
	v_exp_f32_e32 v126, v126
	v_exp_f32_e32 v127, v127
	v_pk_mul_f32 v[120:121], v[120:121], v[174:175]
	v_pk_mul_f32 v[112:113], v[112:113], v[162:163] op_sel_hi:[1,0]
	v_pk_mul_f32 v[122:123], v[122:123], v[162:163] op_sel_hi:[1,0]
	v_pk_mul_f32 v[120:121], v[112:113], v[120:121]
	v_add_f32_e32 v112, 1.0, v126
	v_add_f32_e32 v113, 1.0, v127
	v_mul_f32_e32 v126, 0xbfb8aa3b, v122
	v_mul_f32_e32 v127, 0xbfb8aa3b, v123
	v_exp_f32_e32 v126, v126
	v_exp_f32_e32 v127, v127
	v_rcp_f32_e32 v112, v112
	v_rcp_f32_e32 v113, v113
	v_add_f32_e32 v126, 1.0, v126
	v_add_f32_e32 v127, 1.0, v127
	v_rcp_f32_e32 v126, v126
	v_rcp_f32_e32 v127, v127
	v_lshl_or_b32 v170, s58, 7, v161
	v_pk_mul_f32 v[112:113], v[124:125], v[112:113]
	v_pk_mul_f32 v[118:119], v[118:119], v[162:163] op_sel_hi:[1,0]
	v_ashrrev_i32_e32 v171, 31, v170
	v_pk_mul_f32 v[118:119], v[118:119], v[112:113]
	v_pk_mul_f32 v[112:113], v[122:123], v[126:127]
	v_pk_mul_f32 v[114:115], v[114:115], v[162:163] op_sel_hi:[1,0]
	v_pk_mul_f32 v[108:109], v[108:109], v[160:161] op_sel_hi:[1,0]
	v_pk_mul_f32 v[122:123], v[114:115], v[112:113]
	v_lshlrev_b64 v[112:113], 1, v[170:171]
	v_lshl_add_u64 v[124:125], v[172:173], 0, v[112:113]
	v_cvt_pk_bf16_f32 v114, v116, v117
	v_cvt_pk_bf16_f32 v115, v118, v119
	v_cvt_pk_bf16_f32 v116, v120, v121
	v_cvt_pk_bf16_f32 v117, v122, v123
	global_store_dwordx4 v[124:125], v[114:117], off nt
	v_pk_mul_f32 v[104:105], v[104:105], v[160:161] op_sel_hi:[1,0]
	v_pk_mul_f32 v[100:101], v[100:101], v[160:161] op_sel_hi:[1,0]
	v_mul_f32_e32 v115, 0xbfb8aa3b, v108
	v_exp_f32_e32 v116, v115
	v_mul_f32_e32 v115, 0xbfb8aa3b, v109
	v_exp_f32_e32 v117, v115
	v_mul_f32_e32 v118, 0xbfb8aa3b, v104
	v_add_f32_e32 v116, 1.0, v116
	v_rcp_f32_e32 v116, v116
	v_add_f32_e32 v117, 1.0, v117
	v_mul_f32_e32 v119, 0xbfb8aa3b, v105
	v_rcp_f32_e32 v117, v117
	v_exp_f32_e32 v118, v118
	v_exp_f32_e32 v119, v119
	v_pk_mul_f32 v[96:97], v[96:97], v[160:161] op_sel_hi:[1,0]
	v_pk_mul_f32 v[108:109], v[108:109], v[116:117]
	v_add_f32_e32 v118, 1.0, v118
	v_add_f32_e32 v119, 1.0, v119
	v_pk_mul_f32 v[100:101], v[100:101], v[108:109]
	v_pk_mul_f32 v[108:109], v[110:111], v[160:161] op_sel_hi:[1,0]
	v_rcp_f32_e32 v118, v118
	v_rcp_f32_e32 v119, v119
	v_mul_f32_e32 v110, 0xbfb8aa3b, v108
	v_mul_f32_e32 v111, 0xbfb8aa3b, v109
	v_exp_f32_e32 v110, v110
	v_exp_f32_e32 v111, v111
	v_pk_mul_f32 v[104:105], v[104:105], v[118:119]
	v_pk_mul_f32 v[106:107], v[106:107], v[160:161] op_sel_hi:[1,0]
	v_pk_mul_f32 v[104:105], v[96:97], v[104:105]
	v_add_f32_e32 v96, 1.0, v110
	v_add_f32_e32 v97, 1.0, v111
	v_mul_f32_e32 v110, 0xbfb8aa3b, v106
	v_mul_f32_e32 v111, 0xbfb8aa3b, v107
	v_exp_f32_e32 v110, v110
	v_exp_f32_e32 v111, v111
	v_rcp_f32_e32 v96, v96
	v_rcp_f32_e32 v97, v97
	v_add_f32_e32 v110, 1.0, v110
	v_add_f32_e32 v111, 1.0, v111
	v_rcp_f32_e32 v110, v110
	v_rcp_f32_e32 v111, v111
	v_pk_mul_f32 v[96:97], v[108:109], v[96:97]
	v_pk_mul_f32 v[102:103], v[102:103], v[160:161] op_sel_hi:[1,0]
	v_or_b32_e32 v114, 16, v146
	v_pk_mul_f32 v[102:103], v[102:103], v[96:97]
	v_pk_mul_f32 v[96:97], v[106:107], v[110:111]
	v_pk_mul_f32 v[98:99], v[98:99], v[160:161] op_sel_hi:[1,0]
; __device__ __forceinline__ unsigned pk2(float lo, float hi) { bf16x2_t r = __builtin_convertvector((f32x2_t){lo, hi}, bf16x2_t); return __builtin_bit_cast(unsigned, r); }
; __device__ __forceinline__ float sigmoid_fast(float x) { return __builtin_amdgcn_rcpf(1.0f + __builtin_amdgcn_exp2f(-1.44269504089f * x)); }
;     __device__ __forceinline__ void operator()(const pg8::f32x4 (&acc)[2][2][4][2], const pg8::Unit& u, int wr, int wc, int fr, int fq) const {
;     ...
;                 const float rv = rvs[ai][m];
;                 bf16* p = O + (size_t)(row0 + ai * 128 + m * 16) * FF + col0;
;                 const pg8::f32x4 g0 = acc[ai][0][m][0] * rv, g1 = acc[ai][0][m][1] * rv, u0 = acc[ai][1][m][0] * rv, u1 = acc[ai][1][m][1] * rv;
;                 float r[8];
; #pragma unroll
;                 for (int j = 0; j < 4; ++j) { r[j] = g0[j] * sigmoid_fast(g0[j]) * u0[j]; r[4 + j] = g1[j] * sigmoid_fast(g1[j]) * u1[j]; }
;                 v4u w; w.x = pk2(r[0], r[1]); w.y = pk2(r[2], r[3]); w.z = pk2(r[4], r[5]); w.w = pk2(r[6], r[7]);
;                 __builtin_nontemporal_store(w, (v4u*)p);
	v_mad_i64_i32 v[114:115], s[26:27], v114, s57, v[150:151]
	v_pk_mul_f32 v[106:107], v[98:99], v[96:97]
	v_lshl_add_u64 v[108:109], v[114:115], 0, v[112:113]
	v_cvt_pk_bf16_f32 v96, v100, v101
	v_cvt_pk_bf16_f32 v97, v102, v103
	v_cvt_pk_bf16_f32 v98, v104, v105
	v_cvt_pk_bf16_f32 v99, v106, v107
	v_pk_mul_f32 v[92:93], v[92:93], v[158:159] op_sel_hi:[1,0]
	global_store_dwordx4 v[108:109], v[96:99], off nt
	v_pk_mul_f32 v[88:89], v[88:89], v[158:159] op_sel_hi:[1,0]
	v_pk_mul_f32 v[84:85], v[84:85], v[158:159] op_sel_hi:[1,0]
	v_mul_f32_e32 v97, 0xbfb8aa3b, v92
	v_exp_f32_e32 v98, v97
	v_mul_f32_e32 v97, 0xbfb8aa3b, v93
	v_exp_f32_e32 v99, v97
	v_mul_f32_e32 v100, 0xbfb8aa3b, v88
	v_add_f32_e32 v98, 1.0, v98
	v_rcp_f32_e32 v98, v98
	v_add_f32_e32 v99, 1.0, v99
	v_mul_f32_e32 v101, 0xbfb8aa3b, v89
	v_rcp_f32_e32 v99, v99
	v_exp_f32_e32 v100, v100
	v_exp_f32_e32 v101, v101
	v_pk_mul_f32 v[80:81], v[80:81], v[158:159] op_sel_hi:[1,0]
	v_pk_mul_f32 v[92:93], v[92:93], v[98:99]
	v_add_f32_e32 v100, 1.0, v100
	v_add_f32_e32 v101, 1.0, v101
	v_pk_mul_f32 v[84:85], v[84:85], v[92:93]
	v_pk_mul_f32 v[92:93], v[94:95], v[158:159] op_sel_hi:[1,0]
	v_rcp_f32_e32 v100, v100
	v_rcp_f32_e32 v101, v101
	v_mul_f32_e32 v94, 0xbfb8aa3b, v92
	v_mul_f32_e32 v95, 0xbfb8aa3b, v93
	v_exp_f32_e32 v94, v94
	v_exp_f32_e32 v95, v95
	v_pk_mul_f32 v[88:89], v[88:89], v[100:101]
	v_pk_mul_f32 v[90:91], v[90:91], v[158:159] op_sel_hi:[1,0]
	v_pk_mul_f32 v[88:89], v[80:81], v[88:89]
	v_add_f32_e32 v80, 1.0, v94
	v_add_f32_e32 v81, 1.0, v95
	v_mul_f32_e32 v94, 0xbfb8aa3b, v90
	v_mul_f32_e32 v95, 0xbfb8aa3b, v91
	v_exp_f32_e32 v94, v94
	v_exp_f32_e32 v95, v95
	v_rcp_f32_e32 v80, v80
	v_rcp_f32_e32 v81, v81
	v_add_f32_e32 v94, 1.0, v94
	v_add_f32_e32 v95, 1.0, v95
	v_rcp_f32_e32 v94, v94
	v_rcp_f32_e32 v95, v95
	v_pk_mul_f32 v[80:81], v[92:93], v[80:81]
	v_pk_mul_f32 v[86:87], v[86:87], v[158:159] op_sel_hi:[1,0]
	v_or_b32_e32 v96, 32, v146
	v_pk_mul_f32 v[86:87], v[86:87], v[80:81]
	v_pk_mul_f32 v[80:81], v[90:91], v[94:95]
	v_pk_mul_f32 v[82:83], v[82:83], v[158:159] op_sel_hi:[1,0]
	v_mad_i64_i32 v[96:97], s[26:27], v96, s57, v[150:151]
	v_pk_mul_f32 v[90:91], v[82:83], v[80:81]
	v_lshl_add_u64 v[92:93], v[96:97], 0, v[112:113]
	v_cvt_pk_bf16_f32 v80, v84, v85
	v_cvt_pk_bf16_f32 v81, v86, v87
	v_cvt_pk_bf16_f32 v82, v88, v89
	v_cvt_pk_bf16_f32 v83, v90, v91
	v_pk_mul_f32 v[76:77], v[76:77], v[156:157] op_sel_hi:[1,0]
	global_store_dwordx4 v[92:93], v[80:83], off nt
	v_pk_mul_f32 v[72:73], v[72:73], v[156:157] op_sel_hi:[1,0]
	v_pk_mul_f32 v[68:69], v[68:69], v[156:157] op_sel_hi:[1,0]
	v_mul_f32_e32 v81, 0xbfb8aa3b, v76
	v_exp_f32_e32 v82, v81
	v_mul_f32_e32 v81, 0xbfb8aa3b, v77
	v_exp_f32_e32 v83, v81
	v_mul_f32_e32 v84, 0xbfb8aa3b, v72
	v_add_f32_e32 v82, 1.0, v82
	v_rcp_f32_e32 v82, v82
	v_add_f32_e32 v83, 1.0, v83
	v_mul_f32_e32 v85, 0xbfb8aa3b, v73
	v_rcp_f32_e32 v83, v83
	v_exp_f32_e32 v84, v84
	v_exp_f32_e32 v85, v85
	v_pk_mul_f32 v[64:65], v[64:65], v[156:157] op_sel_hi:[1,0]
	v_pk_mul_f32 v[76:77], v[76:77], v[82:83]
	v_add_f32_e32 v84, 1.0, v84
	v_add_f32_e32 v85, 1.0, v85
	v_pk_mul_f32 v[68:69], v[68:69], v[76:77]
	v_pk_mul_f32 v[76:77], v[78:79], v[156:157] op_sel_hi:[1,0]
	v_rcp_f32_e32 v84, v84
	v_rcp_f32_e32 v85, v85
	v_mul_f32_e32 v78, 0xbfb8aa3b, v76
	v_mul_f32_e32 v79, 0xbfb8aa3b, v77
	v_exp_f32_e32 v78, v78
	v_exp_f32_e32 v79, v79
	v_pk_mul_f32 v[72:73], v[72:73], v[84:85]
	v_pk_mul_f32 v[74:75], v[74:75], v[156:157] op_sel_hi:[1,0]
	v_pk_mul_f32 v[72:73], v[64:65], v[72:73]
	v_add_f32_e32 v64, 1.0, v78
	v_add_f32_e32 v65, 1.0, v79
	v_mul_f32_e32 v78, 0xbfb8aa3b, v74
	v_mul_f32_e32 v79, 0xbfb8aa3b, v75
	v_exp_f32_e32 v78, v78
	v_exp_f32_e32 v79, v79
	v_rcp_f32_e32 v64, v64
	v_rcp_f32_e32 v65, v65
	v_add_f32_e32 v78, 1.0, v78
	v_add_f32_e32 v79, 1.0, v79
	v_rcp_f32_e32 v78, v78
	v_rcp_f32_e32 v79, v79
	v_pk_mul_f32 v[64:65], v[76:77], v[64:65]
	v_pk_mul_f32 v[70:71], v[70:71], v[156:157] op_sel_hi:[1,0]
	v_or_b32_e32 v80, 48, v146
	v_pk_mul_f32 v[70:71], v[70:71], v[64:65]
	v_pk_mul_f32 v[64:65], v[74:75], v[78:79]
	v_pk_mul_f32 v[66:67], v[66:67], v[156:157] op_sel_hi:[1,0]
	v_mad_i64_i32 v[80:81], s[26:27], v80, s57, v[150:151]
	v_pk_mul_f32 v[74:75], v[66:67], v[64:65]
	v_lshl_add_u64 v[76:77], v[80:81], 0, v[112:113]
	v_cvt_pk_bf16_f32 v64, v68, v69
	v_cvt_pk_bf16_f32 v65, v70, v71
	v_cvt_pk_bf16_f32 v66, v72, v73
	v_cvt_pk_bf16_f32 v67, v74, v75
	v_pk_mul_f32 v[60:61], v[60:61], v[154:155] op_sel_hi:[1,0]
	global_store_dwordx4 v[76:77], v[64:67], off nt
	v_pk_mul_f32 v[56:57], v[56:57], v[154:155] op_sel_hi:[1,0]
	v_pk_mul_f32 v[52:53], v[52:53], v[154:155] op_sel_hi:[1,0]
	v_mul_f32_e32 v65, 0xbfb8aa3b, v60
	v_exp_f32_e32 v66, v65
	v_mul_f32_e32 v65, 0xbfb8aa3b, v61
	v_exp_f32_e32 v67, v65
	v_mul_f32_e32 v68, 0xbfb8aa3b, v56
	v_add_f32_e32 v66, 1.0, v66
	v_rcp_f32_e32 v66, v66
	v_add_f32_e32 v67, 1.0, v67
	v_mul_f32_e32 v69, 0xbfb8aa3b, v57
	v_rcp_f32_e32 v67, v67
	v_exp_f32_e32 v68, v68
	v_exp_f32_e32 v69, v69
	v_pk_mul_f32 v[48:49], v[48:49], v[154:155] op_sel_hi:[1,0]
	v_pk_mul_f32 v[60:61], v[60:61], v[66:67]
	v_add_f32_e32 v68, 1.0, v68
	v_add_f32_e32 v69, 1.0, v69
	v_pk_mul_f32 v[52:53], v[52:53], v[60:61]
	v_pk_mul_f32 v[60:61], v[62:63], v[154:155] op_sel_hi:[1,0]
	v_rcp_f32_e32 v68, v68
	v_rcp_f32_e32 v69, v69
	v_mul_f32_e32 v62, 0xbfb8aa3b, v60
	v_mul_f32_e32 v63, 0xbfb8aa3b, v61
	v_exp_f32_e32 v62, v62
	v_exp_f32_e32 v63, v63
	v_pk_mul_f32 v[56:57], v[56:57], v[68:69]
	v_pk_mul_f32 v[58:59], v[58:59], v[154:155] op_sel_hi:[1,0]
	v_pk_mul_f32 v[56:57], v[48:49], v[56:57]
	v_add_f32_e32 v48, 1.0, v62
	v_add_f32_e32 v49, 1.0, v63
; __device__ __forceinline__ unsigned pk2(float lo, float hi) { bf16x2_t r = __builtin_convertvector((f32x2_t){lo, hi}, bf16x2_t); return __builtin_bit_cast(unsigned, r); }
; __device__ __forceinline__ float sigmoid_fast(float x) { return __builtin_amdgcn_rcpf(1.0f + __builtin_amdgcn_exp2f(-1.44269504089f * x)); }
;     __device__ __forceinline__ void operator()(const pg8::f32x4 (&acc)[2][2][4][2], const pg8::Unit& u, int wr, int wc, int fr, int fq) const {
;     ...
;                 const float rv = rvs[ai][m];
;                 bf16* p = O + (size_t)(row0 + ai * 128 + m * 16) * FF + col0;
;                 const pg8::f32x4 g0 = acc[ai][0][m][0] * rv, g1 = acc[ai][0][m][1] * rv, u0 = acc[ai][1][m][0] * rv, u1 = acc[ai][1][m][1] * rv;
;                 float r[8];
; #pragma unroll
;                 for (int j = 0; j < 4; ++j) { r[j] = g0[j] * sigmoid_fast(g0[j]) * u0[j]; r[4 + j] = g1[j] * sigmoid_fast(g1[j]) * u1[j]; }
;                 v4u w; w.x = pk2(r[0], r[1]); w.y = pk2(r[2], r[3]); w.z = pk2(r[4], r[5]); w.w = pk2(r[6], r[7]);
;                 __builtin_nontemporal_store(w, (v4u*)p);
	v_mul_f32_e32 v62, 0xbfb8aa3b, v58
	v_mul_f32_e32 v63, 0xbfb8aa3b, v59
	v_exp_f32_e32 v62, v62
	v_exp_f32_e32 v63, v63
	v_rcp_f32_e32 v48, v48
	v_rcp_f32_e32 v49, v49
	v_add_f32_e32 v62, 1.0, v62
	v_add_f32_e32 v63, 1.0, v63
	v_rcp_f32_e32 v62, v62
	v_rcp_f32_e32 v63, v63
	v_pk_mul_f32 v[48:49], v[60:61], v[48:49]
	v_pk_mul_f32 v[54:55], v[54:55], v[154:155] op_sel_hi:[1,0]
	v_add_u32_e32 v64, 0x80, v146
	v_pk_mul_f32 v[54:55], v[54:55], v[48:49]
	v_pk_mul_f32 v[48:49], v[58:59], v[62:63]
	v_pk_mul_f32 v[50:51], v[50:51], v[154:155] op_sel_hi:[1,0]
	v_mad_i64_i32 v[64:65], s[26:27], v64, s57, v[150:151]
	v_pk_mul_f32 v[58:59], v[50:51], v[48:49]
	v_lshl_add_u64 v[60:61], v[64:65], 0, v[112:113]
	v_cvt_pk_bf16_f32 v48, v52, v53
	v_cvt_pk_bf16_f32 v49, v54, v55
	v_cvt_pk_bf16_f32 v50, v56, v57
	v_cvt_pk_bf16_f32 v51, v58, v59
	v_pk_mul_f32 v[44:45], v[44:45], v[152:153] op_sel_hi:[1,0]
	global_store_dwordx4 v[60:61], v[48:51], off nt
	v_pk_mul_f32 v[40:41], v[40:41], v[152:153] op_sel_hi:[1,0]
	v_pk_mul_f32 v[36:37], v[36:37], v[152:153] op_sel_hi:[1,0]
	v_mul_f32_e32 v49, 0xbfb8aa3b, v44
	v_exp_f32_e32 v50, v49
	v_mul_f32_e32 v49, 0xbfb8aa3b, v45
	v_exp_f32_e32 v51, v49
	v_mul_f32_e32 v52, 0xbfb8aa3b, v40
	v_add_f32_e32 v50, 1.0, v50
	v_rcp_f32_e32 v50, v50
	v_add_f32_e32 v51, 1.0, v51
	v_mul_f32_e32 v53, 0xbfb8aa3b, v41
	v_rcp_f32_e32 v51, v51
	v_exp_f32_e32 v52, v52
	v_exp_f32_e32 v53, v53
	v_pk_mul_f32 v[32:33], v[32:33], v[152:153] op_sel_hi:[1,0]
	v_pk_mul_f32 v[44:45], v[44:45], v[50:51]
	v_add_f32_e32 v52, 1.0, v52
	v_add_f32_e32 v53, 1.0, v53
	v_pk_mul_f32 v[36:37], v[36:37], v[44:45]
	v_pk_mul_f32 v[44:45], v[46:47], v[152:153] op_sel_hi:[1,0]
	v_rcp_f32_e32 v52, v52
	v_rcp_f32_e32 v53, v53
	v_mul_f32_e32 v46, 0xbfb8aa3b, v44
	v_mul_f32_e32 v47, 0xbfb8aa3b, v45
	v_exp_f32_e32 v46, v46
	v_exp_f32_e32 v47, v47
	v_pk_mul_f32 v[40:41], v[40:41], v[52:53]
	v_pk_mul_f32 v[42:43], v[42:43], v[152:153] op_sel_hi:[1,0]
	v_pk_mul_f32 v[40:41], v[32:33], v[40:41]
	v_add_f32_e32 v32, 1.0, v46
	v_add_f32_e32 v33, 1.0, v47
	v_mul_f32_e32 v46, 0xbfb8aa3b, v42
	v_mul_f32_e32 v47, 0xbfb8aa3b, v43
	v_exp_f32_e32 v46, v46
	v_exp_f32_e32 v47, v47
	v_rcp_f32_e32 v32, v32
	v_rcp_f32_e32 v33, v33
	v_add_f32_e32 v46, 1.0, v46
	v_add_f32_e32 v47, 1.0, v47
	v_rcp_f32_e32 v46, v46
	v_rcp_f32_e32 v47, v47
	v_pk_mul_f32 v[32:33], v[44:45], v[32:33]
	v_pk_mul_f32 v[38:39], v[38:39], v[152:153] op_sel_hi:[1,0]
	v_add_u32_e32 v48, 0x90, v146
	v_pk_mul_f32 v[38:39], v[38:39], v[32:33]
	v_pk_mul_f32 v[32:33], v[42:43], v[46:47]
	v_pk_mul_f32 v[34:35], v[34:35], v[152:153] op_sel_hi:[1,0]
	v_mad_i64_i32 v[48:49], s[26:27], v48, s57, v[150:151]
	v_pk_mul_f32 v[42:43], v[34:35], v[32:33]
	v_lshl_add_u64 v[44:45], v[48:49], 0, v[112:113]
	v_cvt_pk_bf16_f32 v32, v36, v37
	v_cvt_pk_bf16_f32 v33, v38, v39
	v_cvt_pk_bf16_f32 v34, v40, v41
	v_cvt_pk_bf16_f32 v35, v42, v43
	v_pk_mul_f32 v[28:29], v[28:29], v[148:149] op_sel_hi:[1,0]
	global_store_dwordx4 v[44:45], v[32:35], off nt
	v_pk_mul_f32 v[24:25], v[24:25], v[148:149] op_sel_hi:[1,0]
	v_pk_mul_f32 v[20:21], v[20:21], v[148:149] op_sel_hi:[1,0]
	v_mul_f32_e32 v33, 0xbfb8aa3b, v28
	v_exp_f32_e32 v34, v33
	v_mul_f32_e32 v33, 0xbfb8aa3b, v29
	v_exp_f32_e32 v35, v33
	v_mul_f32_e32 v36, 0xbfb8aa3b, v24
	v_add_f32_e32 v34, 1.0, v34
	v_rcp_f32_e32 v34, v34
	v_add_f32_e32 v35, 1.0, v35
	v_mul_f32_e32 v37, 0xbfb8aa3b, v25
	v_rcp_f32_e32 v35, v35
	v_exp_f32_e32 v36, v36
	v_exp_f32_e32 v37, v37
	v_pk_mul_f32 v[16:17], v[16:17], v[148:149] op_sel_hi:[1,0]
	v_pk_mul_f32 v[28:29], v[28:29], v[34:35]
; #define PG8_WAIT_V(n) asm volatile("s_waitcnt vmcnt(" #n ")" ::: "memory")
; #define PG8_BAR __builtin_amdgcn_s_barrier()
; __device__ __forceinline__ unsigned pk2(float lo, float hi) { bf16x2_t r = __builtin_convertvector((f32x2_t){lo, hi}, bf16x2_t); return __builtin_bit_cast(unsigned, r); }
; __device__ __forceinline__ float sigmoid_fast(float x) { return __builtin_amdgcn_rcpf(1.0f + __builtin_amdgcn_exp2f(-1.44269504089f * x)); }
;     ...
;         if constexpr (!Epi::AFTER_DRAIN) { E(acc, cur, wr, wc, fr, fq); S.done(cur); }
;         if (!has_next) break;
;         if constexpr (PEEL) { PG8_WAIT_V(8); }
; #pragma unroll
;         for (int a = 0; a < 2; ++a)
; #pragma unroll
;             for (int b = 0; b < 2; ++b)
; #pragma unroll
;                 for (int m = 0; m < 4; ++m)
; #pragma unroll
;                     for (int n = 0; n < 2; ++n) acc[a][b][m][n] = (f32x4){0.f, 0.f, 0.f, 0.f};
;         cur = nxt; cA = nA; cB = nB; ck = nk; ++ui;
;         if constexpr (ALIGN_EPI) { if (wr == 1) PG8_BAR; }
;     __device__ __forceinline__ void operator()(const pg8::f32x4 (&acc)[2][2][4][2], const pg8::Unit& u, int wr, int wc, int fr, int fq) const {
;     ...
;                 const float rv = rvs[ai][m];
;                 bf16* p = O + (size_t)(row0 + ai * 128 + m * 16) * FF + col0;
;                 const pg8::f32x4 g0 = acc[ai][0][m][0] * rv, g1 = acc[ai][0][m][1] * rv, u0 = acc[ai][1][m][0] * rv, u1 = acc[ai][1][m][1] * rv;
;                 float r[8];
; #pragma unroll
;                 for (int j = 0; j < 4; ++j) { r[j] = g0[j] * sigmoid_fast(g0[j]) * u0[j]; r[4 + j] = g1[j] * sigmoid_fast(g1[j]) * u1[j]; }
;                 v4u w; w.x = pk2(r[0], r[1]); w.y = pk2(r[2], r[3]); w.z = pk2(r[4], r[5]); w.w = pk2(r[6], r[7]);
;                 __builtin_nontemporal_store(w, (v4u*)p);
	v_add_f32_e32 v36, 1.0, v36
	v_add_f32_e32 v37, 1.0, v37
	v_pk_mul_f32 v[20:21], v[20:21], v[28:29]
	v_pk_mul_f32 v[28:29], v[30:31], v[148:149] op_sel_hi:[1,0]
	v_rcp_f32_e32 v36, v36
	v_rcp_f32_e32 v37, v37
	v_mul_f32_e32 v30, 0xbfb8aa3b, v28
	v_mul_f32_e32 v31, 0xbfb8aa3b, v29
	v_exp_f32_e32 v30, v30
	v_exp_f32_e32 v31, v31
	v_pk_mul_f32 v[24:25], v[24:25], v[36:37]
	v_pk_mul_f32 v[26:27], v[26:27], v[148:149] op_sel_hi:[1,0]
	v_pk_mul_f32 v[24:25], v[16:17], v[24:25]
	v_add_f32_e32 v16, 1.0, v30
	v_add_f32_e32 v17, 1.0, v31
	v_mul_f32_e32 v30, 0xbfb8aa3b, v26
	v_mul_f32_e32 v31, 0xbfb8aa3b, v27
	v_exp_f32_e32 v30, v30
	v_exp_f32_e32 v31, v31
	v_rcp_f32_e32 v16, v16
	v_rcp_f32_e32 v17, v17
	v_add_f32_e32 v30, 1.0, v30
	v_add_f32_e32 v31, 1.0, v31
	v_rcp_f32_e32 v30, v30
	v_rcp_f32_e32 v31, v31
	v_pk_mul_f32 v[16:17], v[28:29], v[16:17]
	v_pk_mul_f32 v[22:23], v[22:23], v[148:149] op_sel_hi:[1,0]
	v_add_u32_e32 v32, 0xa0, v146
	v_pk_mul_f32 v[22:23], v[22:23], v[16:17]
	v_pk_mul_f32 v[16:17], v[26:27], v[30:31]
	v_pk_mul_f32 v[18:19], v[18:19], v[148:149] op_sel_hi:[1,0]
	v_mad_i64_i32 v[32:33], s[26:27], v32, s57, v[150:151]
	v_pk_mul_f32 v[26:27], v[18:19], v[16:17]
	v_lshl_add_u64 v[28:29], v[32:33], 0, v[112:113]
	v_cvt_pk_bf16_f32 v16, v20, v21
	v_cvt_pk_bf16_f32 v17, v22, v23
	v_cvt_pk_bf16_f32 v18, v24, v25
	v_cvt_pk_bf16_f32 v19, v26, v27
	v_pk_mul_f32 v[12:13], v[12:13], v[144:145] op_sel_hi:[1,0]
	global_store_dwordx4 v[28:29], v[16:19], off nt
	v_pk_mul_f32 v[8:9], v[8:9], v[144:145] op_sel_hi:[1,0]
	v_pk_mul_f32 v[4:5], v[4:5], v[144:145] op_sel_hi:[1,0]
	v_mul_f32_e32 v17, 0xbfb8aa3b, v12
	v_exp_f32_e32 v18, v17
	v_mul_f32_e32 v17, 0xbfb8aa3b, v13
	v_exp_f32_e32 v19, v17
	v_mul_f32_e32 v20, 0xbfb8aa3b, v8
	v_add_f32_e32 v18, 1.0, v18
	v_rcp_f32_e32 v18, v18
	v_add_f32_e32 v19, 1.0, v19
	v_mul_f32_e32 v21, 0xbfb8aa3b, v9
	v_rcp_f32_e32 v19, v19
	v_exp_f32_e32 v20, v20
	v_exp_f32_e32 v21, v21
	v_pk_mul_f32 v[0:1], v[0:1], v[144:145] op_sel_hi:[1,0]
	v_pk_mul_f32 v[12:13], v[12:13], v[18:19]
	v_add_f32_e32 v20, 1.0, v20
	v_add_f32_e32 v21, 1.0, v21
	v_pk_mul_f32 v[4:5], v[4:5], v[12:13]
	v_pk_mul_f32 v[12:13], v[14:15], v[144:145] op_sel_hi:[1,0]
	v_rcp_f32_e32 v20, v20
	v_rcp_f32_e32 v21, v21
	v_mul_f32_e32 v14, 0xbfb8aa3b, v12
	v_mul_f32_e32 v15, 0xbfb8aa3b, v13
	v_exp_f32_e32 v14, v14
	v_exp_f32_e32 v15, v15
	v_pk_mul_f32 v[8:9], v[8:9], v[20:21]
	v_pk_mul_f32 v[10:11], v[10:11], v[144:145] op_sel_hi:[1,0]
	v_pk_mul_f32 v[8:9], v[0:1], v[8:9]
	v_add_f32_e32 v0, 1.0, v14
	v_add_f32_e32 v1, 1.0, v15
	v_mul_f32_e32 v14, 0xbfb8aa3b, v10
	v_mul_f32_e32 v15, 0xbfb8aa3b, v11
	v_exp_f32_e32 v14, v14
	v_exp_f32_e32 v15, v15
	v_rcp_f32_e32 v0, v0
	v_rcp_f32_e32 v1, v1
	v_add_f32_e32 v14, 1.0, v14
	v_add_f32_e32 v15, 1.0, v15
	v_rcp_f32_e32 v14, v14
	v_rcp_f32_e32 v15, v15
	v_pk_mul_f32 v[0:1], v[12:13], v[0:1]
	v_pk_mul_f32 v[6:7], v[6:7], v[144:145] op_sel_hi:[1,0]
	v_add_u32_e32 v16, 0xb0, v146
	v_pk_mul_f32 v[6:7], v[6:7], v[0:1]
	v_pk_mul_f32 v[0:1], v[10:11], v[14:15]
	v_pk_mul_f32 v[2:3], v[2:3], v[144:145] op_sel_hi:[1,0]
	v_mad_i64_i32 v[16:17], s[26:27], v16, s57, v[150:151]
	v_pk_mul_f32 v[10:11], v[2:3], v[0:1]
	v_lshl_add_u64 v[12:13], v[16:17], 0, v[112:113]
	v_cvt_pk_bf16_f32 v0, v4, v5
	v_cvt_pk_bf16_f32 v1, v6, v7
	v_cvt_pk_bf16_f32 v2, v8, v9
	v_cvt_pk_bf16_f32 v3, v10, v11
	s_andn2_b64 vcc, exec, s[0:1]
	s_mov_b64 s[0:1], -1
	global_store_dwordx4 v[12:13], v[0:3], off nt
	s_waitcnt vmcnt(8)
	s_cbranch_vccnz .LBB0_1067
	s_andn2_b64 vcc, exec, s[4:5]
	s_cbranch_vccnz .LBB0_1066
	s_barrier
	s_branch .LBB0_1066

; __device__ __forceinline__ void rs_rows(const LAS unsigned char* lds, const float* rs, int pm, int wr, int fr, float (&rv)[2][4]) {
;     const LAS int* keys = (const LAS int*)(lds + RS_KEY_OFF); const LAS float* tab = (const LAS float*)(lds + RS_TAB_OFF);
;     const int k0 = keys[0], k1 = keys[1], k2 = keys[2], k3 = keys[3];
;     const int idx = (pm == k0) ? 0 : (pm == k1) ? 1 : (pm == k2) ? 2 : (pm == k3) ? 3 : -1;
;     const int rl = wr * 64 + fr;
;     if (idx >= 0) {
; #pragma unroll
;         for (int ai = 0; ai < 2; ++ai)
; #pragma unroll
;             for (int m = 0; m < 4; ++m) rv[ai][m] = tab[idx * 256 + rl + ai * 128 + m * 16];
;     } else {
; #pragma unroll
;         for (int ai = 0; ai < 2; ++ai)
; #pragma unroll
;             for (int m = 0; m < 4; ++m) rv[ai][m] = rs[pm * 256 + rl + ai * 128 + m * 16];
;     }
; }
;     __device__ __forceinline__ void operator()(const pg8::f32x4 (&acc)[2][2][4][2], const pg8::Unit& u, int wr, int wc, int fr, int fq) const {
;     ...
;             for (int m = 0; m < 4; ++m) {
;                 const int row = row0 + ai * 128 + m * 16;
;                 const size_t off = (size_t)row * D + col0;
;                 float s = 0.f;
; #pragma unroll
;                 for (int bj = 0; bj < 2; ++bj) {
;                     float r[8];
; #pragma unroll
;                     for (int j = 0; j < 4; ++j) { r[j] = acc[ai][bj][m][0][j]; r[4 + j] = acc[ai][bj][m][1][j]; }
;                     if (RSCALE) { const float rv = rvs[ai][m];
; #pragma unroll
;                         for (int j = 0; j < 8; ++j) r[j] *= rv; }
;                     if (ACT == 1) {
; #pragma unroll
;                         for (int j = 0; j < 8; ++j) r[j] = sigmoid_fast(r[j]);
;                     }
;                     if (GATE) { const v4u g = gq[m][bj];
;                         r[0] *= bf_lo(g.x); r[1] *= bf_hi(g.x); r[2] *= bf_lo(g.y); r[3] *= bf_hi(g.y); r[4] *= bf_lo(g.z); r[5] *= bf_hi(g.z); r[6] *= bf_lo(g.w); r[7] *= bf_hi(g.w); }
;                     if (ADD) { const v4u g = aq[m][bj];
;                         r[0] += bf_lo(g.x); r[1] += bf_hi(g.x); r[2] += bf_lo(g.y); r[3] += bf_hi(g.y); r[4] += bf_lo(g.z); r[5] += bf_hi(g.z); r[6] += bf_lo(g.w); r[7] += bf_hi(g.w); }
;                     if (PART) {
; #pragma unroll
;                         for (int j = 0; j < 8; ++j) s += r[j] * r[j];
;                     }
.LBB0_1358:
	s_lshl_b32 s25, s40, 8
	v_cmp_lt_i32_e32 vcc, -1, v155
	s_mov_b64 s[40:41], -1
	s_and_b64 vcc, exec, vcc
	v_add_u32_e32 v154, s25, v158
	s_cbranch_vccnz .LBB0_1360
	v_add_u32_e32 v148, s25, v158
	v_ashrrev_i32_e32 v149, 31, v148
	v_lshl_add_u64 v[156:157], v[148:149], 2, s[92:93]
	global_load_dword v152, v[156:157], off
	global_load_dword v153, v[156:157], off offset:64
	global_load_dword v150, v[156:157], off offset:128
	global_load_dword v151, v[156:157], off offset:192
	global_load_dword v146, v[156:157], off offset:512
	global_load_dword v147, v[156:157], off offset:576
	global_load_dword v144, v[156:157], off offset:640
	global_load_dword v145, v[156:157], off offset:704
	s_mov_b64 s[40:41], 0
	v_mov_b64_e32 v[156:157], v[148:149]
	s_waitcnt vmcnt(0)
.LBB0_1360:
	s_andn2_b64 vcc, exec, s[40:41]
	s_cbranch_vccnz .LBB0_1362
	v_lshl_add_u32 v144, v155, 10, v160
	ds_read2_b32 v[152:153], v144 offset1:16
	ds_read2_b32 v[150:151], v144 offset0:32 offset1:48
	ds_read2_b32 v[146:147], v144 offset0:128 offset1:144
	ds_read2_b32 v[144:145], v144 offset0:160 offset1:176
	v_ashrrev_i32_e32 v155, 31, v154
	v_mov_b64_e32 v[156:157], v[154:155]
	v_mov_b32_e32 v148, v154
.LBB0_1362:
	s_waitcnt lgkmcnt(0)
	v_mul_f32_e32 v124, v124, v152
	v_mul_f32_e32 v125, v125, v152
	v_mul_f32_e32 v126, v126, v152
	v_mul_f32_e32 v127, v127, v152
	v_mul_f32_e32 v120, v120, v152
	v_mul_f32_e32 v121, v121, v152
	v_mul_f32_e32 v122, v122, v152
	v_mul_f32_e32 v124, 0xbfb8aa3b, v124
	v_mul_f32_e32 v125, 0xbfb8aa3b, v125
	v_mul_f32_e32 v123, v123, v152
	v_mul_f32_e32 v126, 0xbfb8aa3b, v126
	v_mul_f32_e32 v127, 0xbfb8aa3b, v127
	v_mul_f32_e32 v120, 0xbfb8aa3b, v120
	v_mul_f32_e32 v121, 0xbfb8aa3b, v121
	v_mul_f32_e32 v122, 0xbfb8aa3b, v122
	v_exp_f32_e32 v124, v124
	v_exp_f32_e32 v125, v125
	v_exp_f32_e32 v126, v126
	v_exp_f32_e32 v127, v127
	v_exp_f32_e32 v120, v120
	v_exp_f32_e32 v121, v121
	v_exp_f32_e32 v122, v122
	v_mul_f32_e32 v123, 0xbfb8aa3b, v123
	v_exp_f32_e32 v123, v123
	v_add_f32_e32 v124, 1.0, v124
	v_add_f32_e32 v125, 1.0, v125
	v_add_f32_e32 v126, 1.0, v126
	v_add_f32_e32 v127, 1.0, v127
	v_add_f32_e32 v120, 1.0, v120
	v_add_f32_e32 v121, 1.0, v121
	v_add_f32_e32 v122, 1.0, v122
	v_mul_f32_e32 v112, v112, v152
	v_rcp_f32_e32 v124, v124
	v_rcp_f32_e32 v125, v125
	v_rcp_f32_e32 v126, v126
	v_rcp_f32_e32 v127, v127
	v_rcp_f32_e32 v120, v120
	v_rcp_f32_e32 v121, v121
	v_rcp_f32_e32 v149, v122
	v_add_f32_e32 v122, 1.0, v123
	v_mul_f32_e32 v113, v113, v152
	v_mul_f32_e32 v112, 0xbfb8aa3b, v112
	v_rcp_f32_e32 v165, v122
	v_exp_f32_e32 v112, v112
	v_mul_f32_e32 v113, 0xbfb8aa3b, v113
	v_lshl_or_b32 v154, s66, 8, v161
	v_exp_f32_e32 v113, v113
	v_ashrrev_i32_e32 v155, 31, v154
	v_lshlrev_b64 v[156:157], 11, v[156:157]
	v_cvt_pk_bf16_f32 v122, v124, v125
	v_cvt_pk_bf16_f32 v123, v126, v127
	v_cvt_pk_bf16_f32 v124, v120, v121
	v_lshl_add_u64 v[126:127], s[16:17], 0, v[156:157]
	v_lshlrev_b64 v[120:121], 1, v[154:155]
	v_cvt_pk_bf16_f32 v125, v149, v165
	v_lshl_add_u64 v[126:127], v[126:127], 0, v[120:121]
	v_mul_f32_e32 v114, v114, v152
	v_add_f32_e32 v112, 1.0, v112
	global_store_dwordx4 v[126:127], v[122:125], off
	v_mul_f32_e32 v116, v116, v152
	v_mul_f32_e32 v117, v117, v152
	v_mul_f32_e32 v118, v118, v152
	v_mul_f32_e32 v119, v119, v152
	v_mul_f32_e32 v115, v115, v152
	v_rcp_f32_e32 v122, v112
	v_add_f32_e32 v112, 1.0, v113
	v_mul_f32_e32 v113, 0xbfb8aa3b, v114
	v_mul_f32_e32 v116, 0xbfb8aa3b, v116
	v_mul_f32_e32 v117, 0xbfb8aa3b, v117
	v_mul_f32_e32 v118, 0xbfb8aa3b, v118
	v_mul_f32_e32 v119, 0xbfb8aa3b, v119
	v_exp_f32_e32 v113, v113
	v_mul_f32_e32 v114, 0xbfb8aa3b, v115
	v_exp_f32_e32 v116, v116
	v_exp_f32_e32 v117, v117
	v_exp_f32_e32 v118, v118
	v_exp_f32_e32 v119, v119
	v_exp_f32_e32 v114, v114
	v_rcp_f32_e32 v115, v112
	v_add_f32_e32 v112, 1.0, v113
	v_mul_f32_e32 v104, v104, v153
	v_add_f32_e32 v116, 1.0, v116
	v_add_f32_e32 v117, 1.0, v117
	v_add_f32_e32 v118, 1.0, v118
	v_add_f32_e32 v119, 1.0, v119
	v_rcp_f32_e32 v123, v112
	v_add_f32_e32 v112, 1.0, v114
	v_mul_f32_e32 v105, v105, v153
	v_mul_f32_e32 v104, 0xbfb8aa3b, v104
	v_rcp_f32_e32 v116, v116
	v_rcp_f32_e32 v117, v117
	v_rcp_f32_e32 v118, v118
	v_rcp_f32_e32 v119, v119
	v_rcp_f32_e32 v124, v112
	v_exp_f32_e32 v104, v104
	v_mul_f32_e32 v105, 0xbfb8aa3b, v105
	v_exp_f32_e32 v105, v105
	v_cvt_pk_bf16_f32 v112, v116, v117
	v_cvt_pk_bf16_f32 v113, v118, v119
	v_cvt_pk_bf16_f32 v114, v122, v115
	v_cvt_pk_bf16_f32 v115, v123, v124
	v_mul_f32_e32 v108, v108, v153
	v_mul_f32_e32 v109, v109, v153
	v_mul_f32_e32 v106, v106, v153
	v_add_f32_e32 v104, 1.0, v104
	global_store_dwordx4 v[126:127], v[112:115], off offset:256
	v_mul_f32_e32 v110, v110, v153
	v_mul_f32_e32 v111, v111, v153
	v_mul_f32_e32 v108, 0xbfb8aa3b, v108
	v_mul_f32_e32 v109, 0xbfb8aa3b, v109
	v_mul_f32_e32 v107, v107, v153
	v_rcp_f32_e32 v114, v104
	v_add_f32_e32 v104, 1.0, v105
	v_mul_f32_e32 v105, 0xbfb8aa3b, v106
	v_exp_f32_e32 v108, v108
	v_exp_f32_e32 v109, v109
	v_mul_f32_e32 v110, 0xbfb8aa3b, v110
	v_mul_f32_e32 v111, 0xbfb8aa3b, v111
	v_exp_f32_e32 v105, v105
	v_mul_f32_e32 v106, 0xbfb8aa3b, v107
	v_exp_f32_e32 v110, v110
	v_exp_f32_e32 v111, v111
	v_exp_f32_e32 v106, v106
	v_add_f32_e32 v108, 1.0, v108
	v_add_f32_e32 v109, 1.0, v109
	v_rcp_f32_e32 v107, v104
	v_add_f32_e32 v104, 1.0, v105
	v_mul_f32_e32 v96, v96, v153
	v_rcp_f32_e32 v108, v108
	v_rcp_f32_e32 v109, v109
	v_add_f32_e32 v110, 1.0, v110
	v_add_f32_e32 v111, 1.0, v111
	v_rcp_f32_e32 v115, v104
	v_add_f32_e32 v104, 1.0, v106
	v_mul_f32_e32 v97, v97, v153
	v_mul_f32_e32 v96, 0xbfb8aa3b, v96
	v_or_b32_e32 v112, 16, v148
	v_rcp_f32_e32 v110, v110
; __device__ __forceinline__ float bf_lo(unsigned w) { return __uint_as_float(w << 16); }
; __device__ __forceinline__ float bf_hi(unsigned w) { return __uint_as_float(w & 0xffff0000u); }
; __device__ __forceinline__ unsigned pk2(float lo, float hi) { bf16x2_t r = __builtin_convertvector((f32x2_t){lo, hi}, bf16x2_t); return __builtin_bit_cast(unsigned, r); }
; __device__ __forceinline__ float sigmoid_fast(float x) { return __builtin_amdgcn_rcpf(1.0f + __builtin_amdgcn_exp2f(-1.44269504089f * x)); }
;     __device__ __forceinline__ void operator()(const pg8::f32x4 (&acc)[2][2][4][2], const pg8::Unit& u, int wr, int wc, int fr, int fq) const {
;     ...
;             for (int m = 0; m < 4; ++m) {
;                 const int row = row0 + ai * 128 + m * 16;
;                 const size_t off = (size_t)row * D + col0;
;                 float s = 0.f;
; #pragma unroll
;                 for (int bj = 0; bj < 2; ++bj) {
;                     float r[8];
; #pragma unroll
;                     for (int j = 0; j < 4; ++j) { r[j] = acc[ai][bj][m][0][j]; r[4 + j] = acc[ai][bj][m][1][j]; }
;                     if (RSCALE) { const float rv = rvs[ai][m];
; #pragma unroll
;                         for (int j = 0; j < 8; ++j) r[j] *= rv; }
;                     if (ACT == 1) {
; #pragma unroll
;                         for (int j = 0; j < 8; ++j) r[j] = sigmoid_fast(r[j]);
;                     }
;                     if (GATE) { const v4u g = gq[m][bj];
;                         r[0] *= bf_lo(g.x); r[1] *= bf_hi(g.x); r[2] *= bf_lo(g.y); r[3] *= bf_hi(g.y); r[4] *= bf_lo(g.z); r[5] *= bf_hi(g.z); r[6] *= bf_lo(g.w); r[7] *= bf_hi(g.w); }
;                     if (ADD) { const v4u g = aq[m][bj];
;                         r[0] += bf_lo(g.x); r[1] += bf_hi(g.x); r[2] += bf_lo(g.y); r[3] += bf_hi(g.y); r[4] += bf_lo(g.z); r[5] += bf_hi(g.z); r[6] += bf_lo(g.w); r[7] += bf_hi(g.w); }
;                     if (PART) {
; #pragma unroll
;                         for (int j = 0; j < 8; ++j) s += r[j] * r[j];
;                     }
;                     v4u w; w.x = pk2(r[0], r[1]); w.y = pk2(r[2], r[3]); w.z = pk2(r[4], r[5]); w.w = pk2(r[6], r[7]);
;                     st16_wt(O + off + bj * 128, w);
	v_rcp_f32_e32 v111, v111
	v_rcp_f32_e32 v116, v104
	v_exp_f32_e32 v96, v96
	v_mul_f32_e32 v97, 0xbfb8aa3b, v97
	v_ashrrev_i32_e32 v113, 31, v112
	v_exp_f32_e32 v97, v97
	v_lshlrev_b64 v[112:113], 11, v[112:113]
	v_cvt_pk_bf16_f32 v104, v108, v109
	v_lshl_add_u64 v[108:109], s[16:17], 0, v[112:113]
	v_cvt_pk_bf16_f32 v105, v110, v111
	v_cvt_pk_bf16_f32 v106, v114, v107
	v_cvt_pk_bf16_f32 v107, v115, v116
	v_lshl_add_u64 v[108:109], v[108:109], 0, v[120:121]
	v_mul_f32_e32 v98, v98, v153
	v_add_f32_e32 v96, 1.0, v96
	global_store_dwordx4 v[108:109], v[104:107], off
	v_mul_f32_e32 v100, v100, v153
	v_mul_f32_e32 v101, v101, v153
	v_mul_f32_e32 v102, v102, v153
	v_mul_f32_e32 v103, v103, v153
	v_mul_f32_e32 v99, v99, v153
	v_rcp_f32_e32 v104, v96
	v_add_f32_e32 v96, 1.0, v97
	v_mul_f32_e32 v97, 0xbfb8aa3b, v98
	v_mul_f32_e32 v100, 0xbfb8aa3b, v100
	v_mul_f32_e32 v101, 0xbfb8aa3b, v101
	v_mul_f32_e32 v102, 0xbfb8aa3b, v102
	v_mul_f32_e32 v103, 0xbfb8aa3b, v103
	v_exp_f32_e32 v97, v97
	v_mul_f32_e32 v98, 0xbfb8aa3b, v99
	v_exp_f32_e32 v100, v100
	v_exp_f32_e32 v101, v101
	v_exp_f32_e32 v102, v102
	v_exp_f32_e32 v103, v103
	v_exp_f32_e32 v98, v98
	v_rcp_f32_e32 v99, v96
	v_add_f32_e32 v96, 1.0, v97
	v_mul_f32_e32 v88, v88, v150
	v_add_f32_e32 v100, 1.0, v100
	v_add_f32_e32 v101, 1.0, v101
	v_add_f32_e32 v102, 1.0, v102
	v_add_f32_e32 v103, 1.0, v103
	v_rcp_f32_e32 v105, v96
	v_add_f32_e32 v96, 1.0, v98
	v_mul_f32_e32 v89, v89, v150
	v_mul_f32_e32 v88, 0xbfb8aa3b, v88
	v_rcp_f32_e32 v100, v100
	v_rcp_f32_e32 v101, v101
	v_rcp_f32_e32 v102, v102
	v_rcp_f32_e32 v103, v103
	v_rcp_f32_e32 v106, v96
	v_exp_f32_e32 v88, v88
	v_mul_f32_e32 v89, 0xbfb8aa3b, v89
	v_exp_f32_e32 v89, v89
	v_cvt_pk_bf16_f32 v96, v100, v101
	v_cvt_pk_bf16_f32 v97, v102, v103
	v_cvt_pk_bf16_f32 v98, v104, v99
	v_cvt_pk_bf16_f32 v99, v105, v106
	v_mul_f32_e32 v92, v92, v150
	v_mul_f32_e32 v93, v93, v150
	v_mul_f32_e32 v90, v90, v150
	v_add_f32_e32 v88, 1.0, v88
	global_store_dwordx4 v[108:109], v[96:99], off offset:256
	v_mul_f32_e32 v94, v94, v150
	v_mul_f32_e32 v95, v95, v150
	v_mul_f32_e32 v92, 0xbfb8aa3b, v92
	v_mul_f32_e32 v93, 0xbfb8aa3b, v93
	v_mul_f32_e32 v91, v91, v150
	v_rcp_f32_e32 v98, v88
	v_add_f32_e32 v88, 1.0, v89
	v_mul_f32_e32 v89, 0xbfb8aa3b, v90
	v_exp_f32_e32 v92, v92
	v_exp_f32_e32 v93, v93
	v_mul_f32_e32 v94, 0xbfb8aa3b, v94
	v_mul_f32_e32 v95, 0xbfb8aa3b, v95
	v_exp_f32_e32 v89, v89
	v_mul_f32_e32 v90, 0xbfb8aa3b, v91
	v_exp_f32_e32 v94, v94
	v_exp_f32_e32 v95, v95
	v_exp_f32_e32 v90, v90
	v_add_f32_e32 v92, 1.0, v92
	v_add_f32_e32 v93, 1.0, v93
	v_rcp_f32_e32 v91, v88
	v_add_f32_e32 v88, 1.0, v89
	v_mul_f32_e32 v80, v80, v150
	v_rcp_f32_e32 v92, v92
	v_rcp_f32_e32 v93, v93
	v_add_f32_e32 v94, 1.0, v94
	v_add_f32_e32 v95, 1.0, v95
	v_rcp_f32_e32 v99, v88
	v_add_f32_e32 v88, 1.0, v90
	v_mul_f32_e32 v81, v81, v150
	v_mul_f32_e32 v80, 0xbfb8aa3b, v80
	v_or_b32_e32 v96, 32, v148
	v_rcp_f32_e32 v94, v94
	v_rcp_f32_e32 v95, v95
	v_rcp_f32_e32 v100, v88
	v_exp_f32_e32 v80, v80
	v_mul_f32_e32 v81, 0xbfb8aa3b, v81
	v_ashrrev_i32_e32 v97, 31, v96
	v_exp_f32_e32 v81, v81
	v_lshlrev_b64 v[96:97], 11, v[96:97]
	v_cvt_pk_bf16_f32 v88, v92, v93
	v_lshl_add_u64 v[92:93], s[16:17], 0, v[96:97]
	v_cvt_pk_bf16_f32 v89, v94, v95
	v_cvt_pk_bf16_f32 v90, v98, v91
	v_cvt_pk_bf16_f32 v91, v99, v100
	v_lshl_add_u64 v[92:93], v[92:93], 0, v[120:121]
	v_mul_f32_e32 v82, v82, v150
	v_add_f32_e32 v80, 1.0, v80
	global_store_dwordx4 v[92:93], v[88:91], off
	v_mul_f32_e32 v84, v84, v150
	v_mul_f32_e32 v85, v85, v150
	v_mul_f32_e32 v86, v86, v150
	v_mul_f32_e32 v87, v87, v150
	v_mul_f32_e32 v83, v83, v150
	v_rcp_f32_e32 v88, v80
	v_add_f32_e32 v80, 1.0, v81
	v_mul_f32_e32 v81, 0xbfb8aa3b, v82
	v_mul_f32_e32 v84, 0xbfb8aa3b, v84
	v_mul_f32_e32 v85, 0xbfb8aa3b, v85
	v_mul_f32_e32 v86, 0xbfb8aa3b, v86
	v_mul_f32_e32 v87, 0xbfb8aa3b, v87
	v_exp_f32_e32 v81, v81
	v_mul_f32_e32 v82, 0xbfb8aa3b, v83
	v_exp_f32_e32 v84, v84
	v_exp_f32_e32 v85, v85
	v_exp_f32_e32 v86, v86
	v_exp_f32_e32 v87, v87
	v_exp_f32_e32 v82, v82
	v_rcp_f32_e32 v83, v80
	v_add_f32_e32 v80, 1.0, v81
	v_mul_f32_e32 v72, v72, v151
	v_add_f32_e32 v84, 1.0, v84
	v_add_f32_e32 v85, 1.0, v85
	v_add_f32_e32 v86, 1.0, v86
	v_add_f32_e32 v87, 1.0, v87
	v_rcp_f32_e32 v89, v80
	v_add_f32_e32 v80, 1.0, v82
	v_mul_f32_e32 v73, v73, v151
	v_mul_f32_e32 v72, 0xbfb8aa3b, v72
	v_rcp_f32_e32 v84, v84
	v_rcp_f32_e32 v85, v85
	v_rcp_f32_e32 v86, v86
	v_rcp_f32_e32 v87, v87
	v_rcp_f32_e32 v90, v80
	v_exp_f32_e32 v72, v72
	v_mul_f32_e32 v73, 0xbfb8aa3b, v73
	v_exp_f32_e32 v73, v73
	v_cvt_pk_bf16_f32 v80, v84, v85
	v_cvt_pk_bf16_f32 v81, v86, v87
	v_cvt_pk_bf16_f32 v82, v88, v83
	v_cvt_pk_bf16_f32 v83, v89, v90
	v_mul_f32_e32 v76, v76, v151
	v_mul_f32_e32 v77, v77, v151
	v_mul_f32_e32 v74, v74, v151
	v_add_f32_e32 v72, 1.0, v72
	global_store_dwordx4 v[92:93], v[80:83], off offset:256
	v_mul_f32_e32 v78, v78, v151
	v_mul_f32_e32 v79, v79, v151
	v_mul_f32_e32 v76, 0xbfb8aa3b, v76
	v_mul_f32_e32 v77, 0xbfb8aa3b, v77
	v_mul_f32_e32 v75, v75, v151
	v_rcp_f32_e32 v82, v72
	v_add_f32_e32 v72, 1.0, v73
	v_mul_f32_e32 v73, 0xbfb8aa3b, v74
	v_exp_f32_e32 v76, v76
	v_exp_f32_e32 v77, v77
	v_mul_f32_e32 v78, 0xbfb8aa3b, v78
	v_mul_f32_e32 v79, 0xbfb8aa3b, v79
	v_exp_f32_e32 v73, v73
	v_mul_f32_e32 v74, 0xbfb8aa3b, v75
	v_exp_f32_e32 v78, v78
	v_exp_f32_e32 v79, v79
	v_exp_f32_e32 v74, v74
	v_add_f32_e32 v76, 1.0, v76
	v_add_f32_e32 v77, 1.0, v77
	v_rcp_f32_e32 v75, v72
	v_add_f32_e32 v72, 1.0, v73
	v_mul_f32_e32 v64, v64, v151
	v_rcp_f32_e32 v76, v76
	v_rcp_f32_e32 v77, v77
	v_add_f32_e32 v78, 1.0, v78
	v_add_f32_e32 v79, 1.0, v79
	v_rcp_f32_e32 v83, v72
; __device__ __forceinline__ float bf_lo(unsigned w) { return __uint_as_float(w << 16); }
; __device__ __forceinline__ float bf_hi(unsigned w) { return __uint_as_float(w & 0xffff0000u); }
; __device__ __forceinline__ unsigned pk2(float lo, float hi) { bf16x2_t r = __builtin_convertvector((f32x2_t){lo, hi}, bf16x2_t); return __builtin_bit_cast(unsigned, r); }
; __device__ __forceinline__ float sigmoid_fast(float x) { return __builtin_amdgcn_rcpf(1.0f + __builtin_amdgcn_exp2f(-1.44269504089f * x)); }
;     __device__ __forceinline__ void operator()(const pg8::f32x4 (&acc)[2][2][4][2], const pg8::Unit& u, int wr, int wc, int fr, int fq) const {
;     ...
;             for (int m = 0; m < 4; ++m) {
;                 const int row = row0 + ai * 128 + m * 16;
;                 const size_t off = (size_t)row * D + col0;
;                 float s = 0.f;
; #pragma unroll
;                 for (int bj = 0; bj < 2; ++bj) {
;                     float r[8];
; #pragma unroll
;                     for (int j = 0; j < 4; ++j) { r[j] = acc[ai][bj][m][0][j]; r[4 + j] = acc[ai][bj][m][1][j]; }
;                     if (RSCALE) { const float rv = rvs[ai][m];
; #pragma unroll
;                         for (int j = 0; j < 8; ++j) r[j] *= rv; }
;                     if (ACT == 1) {
; #pragma unroll
;                         for (int j = 0; j < 8; ++j) r[j] = sigmoid_fast(r[j]);
;                     }
;                     if (GATE) { const v4u g = gq[m][bj];
;                         r[0] *= bf_lo(g.x); r[1] *= bf_hi(g.x); r[2] *= bf_lo(g.y); r[3] *= bf_hi(g.y); r[4] *= bf_lo(g.z); r[5] *= bf_hi(g.z); r[6] *= bf_lo(g.w); r[7] *= bf_hi(g.w); }
;                     if (ADD) { const v4u g = aq[m][bj];
;                         r[0] += bf_lo(g.x); r[1] += bf_hi(g.x); r[2] += bf_lo(g.y); r[3] += bf_hi(g.y); r[4] += bf_lo(g.z); r[5] += bf_hi(g.z); r[6] += bf_lo(g.w); r[7] += bf_hi(g.w); }
;                     if (PART) {
; #pragma unroll
;                         for (int j = 0; j < 8; ++j) s += r[j] * r[j];
;                     }
;                     v4u w; w.x = pk2(r[0], r[1]); w.y = pk2(r[2], r[3]); w.z = pk2(r[4], r[5]); w.w = pk2(r[6], r[7]);
;                     st16_wt(O + off + bj * 128, w);
	v_add_f32_e32 v72, 1.0, v74
	v_mul_f32_e32 v65, v65, v151
	v_mul_f32_e32 v64, 0xbfb8aa3b, v64
	v_or_b32_e32 v80, 48, v148
	v_rcp_f32_e32 v78, v78
	v_rcp_f32_e32 v79, v79
	v_rcp_f32_e32 v84, v72
	v_exp_f32_e32 v64, v64
	v_mul_f32_e32 v65, 0xbfb8aa3b, v65
	v_ashrrev_i32_e32 v81, 31, v80
	v_exp_f32_e32 v65, v65
	v_lshlrev_b64 v[80:81], 11, v[80:81]
	v_cvt_pk_bf16_f32 v72, v76, v77
	v_lshl_add_u64 v[76:77], s[16:17], 0, v[80:81]
	v_cvt_pk_bf16_f32 v73, v78, v79
	v_cvt_pk_bf16_f32 v74, v82, v75
	v_cvt_pk_bf16_f32 v75, v83, v84
	v_lshl_add_u64 v[76:77], v[76:77], 0, v[120:121]
	v_mul_f32_e32 v66, v66, v151
	v_add_f32_e32 v64, 1.0, v64
	global_store_dwordx4 v[76:77], v[72:75], off
	v_mul_f32_e32 v68, v68, v151
	v_mul_f32_e32 v69, v69, v151
	v_mul_f32_e32 v70, v70, v151
	v_mul_f32_e32 v71, v71, v151
	v_mul_f32_e32 v67, v67, v151
	v_rcp_f32_e32 v72, v64
	v_add_f32_e32 v64, 1.0, v65
	v_mul_f32_e32 v65, 0xbfb8aa3b, v66
	v_mul_f32_e32 v68, 0xbfb8aa3b, v68
	v_mul_f32_e32 v69, 0xbfb8aa3b, v69
	v_mul_f32_e32 v70, 0xbfb8aa3b, v70
	v_mul_f32_e32 v71, 0xbfb8aa3b, v71
	v_exp_f32_e32 v65, v65
	v_mul_f32_e32 v66, 0xbfb8aa3b, v67
	v_exp_f32_e32 v68, v68
	v_exp_f32_e32 v69, v69
	v_exp_f32_e32 v70, v70
	v_exp_f32_e32 v71, v71
	v_exp_f32_e32 v66, v66
	v_mul_f32_e32 v60, v60, v146
	v_mul_f32_e32 v61, v61, v146
	v_mul_f32_e32 v56, v56, v146
	v_mul_f32_e32 v57, v57, v146
	v_mul_f32_e32 v60, 0xbfb8aa3b, v60
	v_mul_f32_e32 v61, 0xbfb8aa3b, v61
	v_mul_f32_e32 v56, 0xbfb8aa3b, v56
	v_mul_f32_e32 v57, 0xbfb8aa3b, v57
	v_rcp_f32_e32 v67, v64
	v_add_f32_e32 v64, 1.0, v65
	v_mul_f32_e32 v58, v58, v146
	v_exp_f32_e32 v60, v60
	v_exp_f32_e32 v61, v61
	v_exp_f32_e32 v56, v56
	v_exp_f32_e32 v57, v57
	v_add_f32_e32 v68, 1.0, v68
	v_add_f32_e32 v69, 1.0, v69
	v_add_f32_e32 v70, 1.0, v70
	v_add_f32_e32 v71, 1.0, v71
	v_rcp_f32_e32 v73, v64
	v_add_f32_e32 v64, 1.0, v66
	v_mul_f32_e32 v59, v59, v146
	v_mul_f32_e32 v58, 0xbfb8aa3b, v58
	v_rcp_f32_e32 v68, v68
	v_rcp_f32_e32 v69, v69
	v_rcp_f32_e32 v70, v70
	v_rcp_f32_e32 v71, v71
	v_rcp_f32_e32 v74, v64
	v_mul_f32_e32 v62, v62, v146
	v_mul_f32_e32 v63, v63, v146
	v_exp_f32_e32 v58, v58
	v_mul_f32_e32 v59, 0xbfb8aa3b, v59
	v_mul_f32_e32 v62, 0xbfb8aa3b, v62
	v_mul_f32_e32 v63, 0xbfb8aa3b, v63
	v_exp_f32_e32 v59, v59
	v_add_f32_e32 v60, 1.0, v60
	v_add_f32_e32 v61, 1.0, v61
	v_exp_f32_e32 v62, v62
	v_exp_f32_e32 v63, v63
	v_add_f32_e32 v56, 1.0, v56
	v_add_f32_e32 v57, 1.0, v57
	v_rcp_f32_e32 v60, v60
	v_rcp_f32_e32 v61, v61
	v_rcp_f32_e32 v56, v56
	v_rcp_f32_e32 v57, v57
	v_cvt_pk_bf16_f32 v64, v68, v69
	v_cvt_pk_bf16_f32 v65, v70, v71
	v_cvt_pk_bf16_f32 v66, v72, v67
	v_cvt_pk_bf16_f32 v67, v73, v74
	v_add_f32_e32 v58, 1.0, v58
	global_store_dwordx4 v[76:77], v[64:67], off offset:256
	v_mul_f32_e32 v48, v48, v146
	v_add_f32_e32 v62, 1.0, v62
	v_rcp_f32_e32 v64, v58
	v_add_f32_e32 v58, 1.0, v59
	v_add_f32_e32 v63, 1.0, v63
	v_rcp_f32_e32 v65, v58
	v_ashrrev_i32_e32 v149, 31, v148
	v_mul_f32_e32 v49, v49, v146
	v_mul_f32_e32 v48, 0xbfb8aa3b, v48
	v_rcp_f32_e32 v62, v62
	v_rcp_f32_e32 v63, v63
	v_cvt_pk_bf16_f32 v58, v60, v61
	v_cvt_pk_bf16_f32 v60, v56, v57
	v_lshlrev_b64 v[56:57], 11, v[148:149]
	v_exp_f32_e32 v48, v48
	v_mul_f32_e32 v49, 0xbfb8aa3b, v49
	v_lshl_add_u64 v[56:57], s[16:17], 0, v[56:57]
	v_exp_f32_e32 v49, v49
	v_lshl_add_u64 v[56:57], v[56:57], 0, v[120:121]
	v_cvt_pk_bf16_f32 v61, v64, v65
	v_add_co_u32_e32 v64, vcc, s62, v56
	v_cvt_pk_bf16_f32 v59, v62, v63
	s_nop 0
	v_addc_co_u32_e32 v65, vcc, 0, v57, vcc
	v_mul_f32_e32 v50, v50, v146
	v_add_f32_e32 v48, 1.0, v48
	global_store_dwordx4 v[64:65], v[58:61], off
	v_mul_f32_e32 v52, v52, v146
	v_mul_f32_e32 v53, v53, v146
	v_mul_f32_e32 v54, v54, v146
	v_mul_f32_e32 v55, v55, v146
	v_mul_f32_e32 v51, v51, v146
	v_rcp_f32_e32 v58, v48
	v_add_f32_e32 v48, 1.0, v49
	v_mul_f32_e32 v49, 0xbfb8aa3b, v50
	v_mul_f32_e32 v52, 0xbfb8aa3b, v52
	v_mul_f32_e32 v53, 0xbfb8aa3b, v53
	v_mul_f32_e32 v54, 0xbfb8aa3b, v54
	v_mul_f32_e32 v55, 0xbfb8aa3b, v55
	v_exp_f32_e32 v49, v49
	v_mul_f32_e32 v50, 0xbfb8aa3b, v51
	v_exp_f32_e32 v52, v52
	v_exp_f32_e32 v53, v53
	v_exp_f32_e32 v54, v54
	v_exp_f32_e32 v55, v55
	v_exp_f32_e32 v50, v50
	v_rcp_f32_e32 v51, v48
	v_add_f32_e32 v48, 1.0, v49
	v_mul_f32_e32 v40, v40, v147
	v_add_f32_e32 v52, 1.0, v52
	v_add_f32_e32 v53, 1.0, v53
	v_add_f32_e32 v54, 1.0, v54
	v_add_f32_e32 v55, 1.0, v55
	v_rcp_f32_e32 v59, v48
	v_add_f32_e32 v48, 1.0, v50
	v_mul_f32_e32 v41, v41, v147
	v_mul_f32_e32 v40, 0xbfb8aa3b, v40
	v_rcp_f32_e32 v52, v52
	v_rcp_f32_e32 v53, v53
	v_rcp_f32_e32 v54, v54
	v_rcp_f32_e32 v55, v55
	v_rcp_f32_e32 v60, v48
	v_exp_f32_e32 v40, v40
	v_mul_f32_e32 v41, 0xbfb8aa3b, v41
	v_exp_f32_e32 v41, v41
	v_lshl_add_u64 v[62:63], v[56:57], 0, s[4:5]
	v_cvt_pk_bf16_f32 v48, v52, v53
	v_cvt_pk_bf16_f32 v49, v54, v55
	v_cvt_pk_bf16_f32 v50, v58, v51
	v_cvt_pk_bf16_f32 v51, v59, v60
	v_mul_f32_e32 v46, v46, v147
	v_mul_f32_e32 v47, v47, v147
	v_mul_f32_e32 v42, v42, v147
	v_add_f32_e32 v40, 1.0, v40
	global_store_dwordx4 v[62:63], v[48:51], off offset:256
	v_mul_f32_e32 v44, v44, v147
	v_mul_f32_e32 v45, v45, v147
	v_mul_f32_e32 v43, v43, v147
	v_mul_f32_e32 v46, 0xbfb8aa3b, v46
	v_mul_f32_e32 v47, 0xbfb8aa3b, v47
	v_rcp_f32_e32 v48, v40
	v_add_f32_e32 v40, 1.0, v41
	v_mul_f32_e32 v41, 0xbfb8aa3b, v42
	v_mul_f32_e32 v44, 0xbfb8aa3b, v44
	v_mul_f32_e32 v45, 0xbfb8aa3b, v45
	v_exp_f32_e32 v46, v46
	v_exp_f32_e32 v47, v47
	v_exp_f32_e32 v41, v41
	v_mul_f32_e32 v42, 0xbfb8aa3b, v43
	v_exp_f32_e32 v44, v44
	v_exp_f32_e32 v45, v45
	v_exp_f32_e32 v42, v42
	v_add_f32_e32 v46, 1.0, v46
	v_add_f32_e32 v47, 1.0, v47
	v_rcp_f32_e32 v43, v40
	v_add_f32_e32 v40, 1.0, v41
; __device__ __forceinline__ float bf_lo(unsigned w) { return __uint_as_float(w << 16); }
; __device__ __forceinline__ float bf_hi(unsigned w) { return __uint_as_float(w & 0xffff0000u); }
; __device__ __forceinline__ unsigned pk2(float lo, float hi) { bf16x2_t r = __builtin_convertvector((f32x2_t){lo, hi}, bf16x2_t); return __builtin_bit_cast(unsigned, r); }
; __device__ __forceinline__ float sigmoid_fast(float x) { return __builtin_amdgcn_rcpf(1.0f + __builtin_amdgcn_exp2f(-1.44269504089f * x)); }
;     __device__ __forceinline__ void operator()(const pg8::f32x4 (&acc)[2][2][4][2], const pg8::Unit& u, int wr, int wc, int fr, int fq) const {
;     ...
;             for (int m = 0; m < 4; ++m) {
;                 const int row = row0 + ai * 128 + m * 16;
;                 const size_t off = (size_t)row * D + col0;
;                 float s = 0.f;
; #pragma unroll
;                 for (int bj = 0; bj < 2; ++bj) {
;                     float r[8];
; #pragma unroll
;                     for (int j = 0; j < 4; ++j) { r[j] = acc[ai][bj][m][0][j]; r[4 + j] = acc[ai][bj][m][1][j]; }
;                     if (RSCALE) { const float rv = rvs[ai][m];
; #pragma unroll
;                         for (int j = 0; j < 8; ++j) r[j] *= rv; }
;                     if (ACT == 1) {
; #pragma unroll
;                         for (int j = 0; j < 8; ++j) r[j] = sigmoid_fast(r[j]);
;                     }
;                     if (GATE) { const v4u g = gq[m][bj];
;                         r[0] *= bf_lo(g.x); r[1] *= bf_hi(g.x); r[2] *= bf_lo(g.y); r[3] *= bf_hi(g.y); r[4] *= bf_lo(g.z); r[5] *= bf_hi(g.z); r[6] *= bf_lo(g.w); r[7] *= bf_hi(g.w); }
;                     if (ADD) { const v4u g = aq[m][bj];
;                         r[0] += bf_lo(g.x); r[1] += bf_hi(g.x); r[2] += bf_lo(g.y); r[3] += bf_hi(g.y); r[4] += bf_lo(g.z); r[5] += bf_hi(g.z); r[6] += bf_lo(g.w); r[7] += bf_hi(g.w); }
;                     if (PART) {
; #pragma unroll
;                         for (int j = 0; j < 8; ++j) s += r[j] * r[j];
;                     }
;                     v4u w; w.x = pk2(r[0], r[1]); w.y = pk2(r[2], r[3]); w.z = pk2(r[4], r[5]); w.w = pk2(r[6], r[7]);
;                     st16_wt(O + off + bj * 128, w);
	v_mul_f32_e32 v32, v32, v147
	v_add_f32_e32 v44, 1.0, v44
	v_add_f32_e32 v45, 1.0, v45
	v_rcp_f32_e32 v46, v46
	v_rcp_f32_e32 v47, v47
	v_rcp_f32_e32 v49, v40
	v_add_f32_e32 v40, 1.0, v42
	v_mul_f32_e32 v33, v33, v147
	v_mul_f32_e32 v32, 0xbfb8aa3b, v32
	v_rcp_f32_e32 v44, v44
	v_rcp_f32_e32 v45, v45
	v_rcp_f32_e32 v50, v40
	v_exp_f32_e32 v32, v32
	v_mul_f32_e32 v33, 0xbfb8aa3b, v33
	v_exp_f32_e32 v33, v33
	v_cvt_pk_bf16_f32 v41, v46, v47
	v_add_co_u32_e32 v46, vcc, s63, v56
	v_cvt_pk_bf16_f32 v40, v44, v45
	v_cvt_pk_bf16_f32 v42, v48, v43
	v_cvt_pk_bf16_f32 v43, v49, v50
	v_addc_co_u32_e32 v47, vcc, 0, v57, vcc
	v_mul_f32_e32 v34, v34, v147
	v_add_f32_e32 v32, 1.0, v32
	global_store_dwordx4 v[46:47], v[40:43], off
	v_mul_f32_e32 v36, v36, v147
	v_mul_f32_e32 v37, v37, v147
	v_mul_f32_e32 v38, v38, v147
	v_mul_f32_e32 v39, v39, v147
	v_mul_f32_e32 v35, v35, v147
	v_rcp_f32_e32 v40, v32
	v_add_f32_e32 v32, 1.0, v33
	v_mul_f32_e32 v33, 0xbfb8aa3b, v34
	v_mul_f32_e32 v36, 0xbfb8aa3b, v36
	v_mul_f32_e32 v37, 0xbfb8aa3b, v37
	v_mul_f32_e32 v38, 0xbfb8aa3b, v38
	v_mul_f32_e32 v39, 0xbfb8aa3b, v39
	v_exp_f32_e32 v33, v33
	v_mul_f32_e32 v34, 0xbfb8aa3b, v35
	v_exp_f32_e32 v36, v36
	v_exp_f32_e32 v37, v37
	v_exp_f32_e32 v38, v38
	v_exp_f32_e32 v39, v39
	v_exp_f32_e32 v34, v34
	v_rcp_f32_e32 v35, v32
	v_add_f32_e32 v32, 1.0, v33
	v_mul_f32_e32 v24, v24, v144
	v_add_f32_e32 v36, 1.0, v36
	v_add_f32_e32 v37, 1.0, v37
	v_add_f32_e32 v38, 1.0, v38
	v_add_f32_e32 v39, 1.0, v39
	v_rcp_f32_e32 v41, v32
	v_add_f32_e32 v32, 1.0, v34
	v_mul_f32_e32 v25, v25, v144
	v_mul_f32_e32 v24, 0xbfb8aa3b, v24
	v_rcp_f32_e32 v36, v36
	v_rcp_f32_e32 v37, v37
	v_rcp_f32_e32 v38, v38
	v_rcp_f32_e32 v39, v39
	v_rcp_f32_e32 v42, v32
	v_exp_f32_e32 v24, v24
	v_mul_f32_e32 v25, 0xbfb8aa3b, v25
	v_exp_f32_e32 v25, v25
	v_lshl_add_u64 v[44:45], v[56:57], 0, s[12:13]
	v_cvt_pk_bf16_f32 v32, v36, v37
	v_cvt_pk_bf16_f32 v33, v38, v39
	v_cvt_pk_bf16_f32 v34, v40, v35
	v_cvt_pk_bf16_f32 v35, v41, v42
	v_mul_f32_e32 v30, v30, v144
	v_mul_f32_e32 v31, v31, v144
	v_mul_f32_e32 v26, v26, v144
	v_add_f32_e32 v24, 1.0, v24
	global_store_dwordx4 v[44:45], v[32:35], off offset:256
	v_mul_f32_e32 v28, v28, v144
	v_mul_f32_e32 v29, v29, v144
	v_mul_f32_e32 v27, v27, v144
	v_mul_f32_e32 v30, 0xbfb8aa3b, v30
	v_mul_f32_e32 v31, 0xbfb8aa3b, v31
	v_rcp_f32_e32 v32, v24
	v_add_f32_e32 v24, 1.0, v25
	v_mul_f32_e32 v25, 0xbfb8aa3b, v26
	v_mul_f32_e32 v28, 0xbfb8aa3b, v28
	v_mul_f32_e32 v29, 0xbfb8aa3b, v29
	v_exp_f32_e32 v30, v30
	v_exp_f32_e32 v31, v31
	v_exp_f32_e32 v25, v25
	v_mul_f32_e32 v26, 0xbfb8aa3b, v27
	v_exp_f32_e32 v28, v28
	v_exp_f32_e32 v29, v29
	v_exp_f32_e32 v26, v26
	v_add_f32_e32 v30, 1.0, v30
	v_add_f32_e32 v31, 1.0, v31
	v_rcp_f32_e32 v27, v24
	v_add_f32_e32 v24, 1.0, v25
	v_mul_f32_e32 v16, v16, v144
	v_add_f32_e32 v28, 1.0, v28
	v_add_f32_e32 v29, 1.0, v29
	v_rcp_f32_e32 v30, v30
	v_rcp_f32_e32 v31, v31
	v_rcp_f32_e32 v33, v24
	v_add_f32_e32 v24, 1.0, v26
	v_mul_f32_e32 v17, v17, v144
	v_mul_f32_e32 v16, 0xbfb8aa3b, v16
	v_rcp_f32_e32 v28, v28
	v_rcp_f32_e32 v29, v29
	v_rcp_f32_e32 v34, v24
	v_exp_f32_e32 v16, v16
	v_mul_f32_e32 v17, 0xbfb8aa3b, v17
	v_exp_f32_e32 v17, v17
	v_cvt_pk_bf16_f32 v25, v30, v31
	v_add_co_u32_e32 v30, vcc, s64, v56
	v_cvt_pk_bf16_f32 v24, v28, v29
	v_cvt_pk_bf16_f32 v26, v32, v27
	v_cvt_pk_bf16_f32 v27, v33, v34
	v_addc_co_u32_e32 v31, vcc, 0, v57, vcc
	v_mul_f32_e32 v18, v18, v144
	v_add_f32_e32 v16, 1.0, v16
	global_store_dwordx4 v[30:31], v[24:27], off
	v_mul_f32_e32 v20, v20, v144
	v_mul_f32_e32 v21, v21, v144
	v_mul_f32_e32 v22, v22, v144
	v_mul_f32_e32 v23, v23, v144
	v_mul_f32_e32 v19, v19, v144
	v_rcp_f32_e32 v24, v16
	v_add_f32_e32 v16, 1.0, v17
	v_mul_f32_e32 v17, 0xbfb8aa3b, v18
; #define PG8_WAIT_V(n) asm volatile("s_waitcnt vmcnt(" #n ")" ::: "memory")
;     ...
;         if constexpr (!Epi::AFTER_DRAIN) { E(acc, cur, wr, wc, fr, fq); S.done(cur); }
;         if (!has_next) break;
;         if constexpr (PEEL) { PG8_WAIT_V(8); }
; #pragma unroll
;         for (int a = 0; a < 2; ++a)
; #pragma unroll
;             for (int b = 0; b < 2; ++b)
; #pragma unroll
;                 for (int m = 0; m < 4; ++m)
; #pragma unroll
;                     for (int n = 0; n < 2; ++n) acc[a][b][m][n] = (f32x4){0.f, 0.f, 0.f, 0.f};
;         cur = nxt; cA = nA; cB = nB; ck = nk; ++ui;
;         if constexpr (ALIGN_EPI) { if (wr == 1) PG8_BAR; }
;     __device__ __forceinline__ void operator()(const pg8::f32x4 (&acc)[2][2][4][2], const pg8::Unit& u, int wr, int wc, int fr, int fq) const {
;     ...
;             for (int m = 0; m < 4; ++m) {
;                 const int row = row0 + ai * 128 + m * 16;
;                 const size_t off = (size_t)row * D + col0;
;                 float s = 0.f;
; #pragma unroll
;                 for (int bj = 0; bj < 2; ++bj) {
;                     float r[8];
; #pragma unroll
;                     for (int j = 0; j < 4; ++j) { r[j] = acc[ai][bj][m][0][j]; r[4 + j] = acc[ai][bj][m][1][j]; }
;                     if (RSCALE) { const float rv = rvs[ai][m];
; #pragma unroll
;                         for (int j = 0; j < 8; ++j) r[j] *= rv; }
;                     if (ACT == 1) {
; #pragma unroll
;                         for (int j = 0; j < 8; ++j) r[j] = sigmoid_fast(r[j]);
;                     }
;                     if (GATE) { const v4u g = gq[m][bj];
;                         r[0] *= bf_lo(g.x); r[1] *= bf_hi(g.x); r[2] *= bf_lo(g.y); r[3] *= bf_hi(g.y); r[4] *= bf_lo(g.z); r[5] *= bf_hi(g.z); r[6] *= bf_lo(g.w); r[7] *= bf_hi(g.w); }
;                     if (ADD) { const v4u g = aq[m][bj];
;                         r[0] += bf_lo(g.x); r[1] += bf_hi(g.x); r[2] += bf_lo(g.y); r[3] += bf_hi(g.y); r[4] += bf_lo(g.z); r[5] += bf_hi(g.z); r[6] += bf_lo(g.w); r[7] += bf_hi(g.w); }
;                     if (PART) {
; #pragma unroll
;                         for (int j = 0; j < 8; ++j) s += r[j] * r[j];
;                     }
;                     v4u w; w.x = pk2(r[0], r[1]); w.y = pk2(r[2], r[3]); w.z = pk2(r[4], r[5]); w.w = pk2(r[6], r[7]);
;                     st16_wt(O + off + bj * 128, w);
	v_mul_f32_e32 v20, 0xbfb8aa3b, v20
	v_mul_f32_e32 v21, 0xbfb8aa3b, v21
	v_mul_f32_e32 v22, 0xbfb8aa3b, v22
	v_mul_f32_e32 v23, 0xbfb8aa3b, v23
	v_exp_f32_e32 v17, v17
	v_mul_f32_e32 v18, 0xbfb8aa3b, v19
	v_exp_f32_e32 v20, v20
	v_exp_f32_e32 v21, v21
	v_exp_f32_e32 v22, v22
	v_exp_f32_e32 v23, v23
	v_exp_f32_e32 v18, v18
	v_rcp_f32_e32 v19, v16
	v_add_f32_e32 v16, 1.0, v17
	v_mul_f32_e32 v8, v8, v145
	v_add_f32_e32 v20, 1.0, v20
	v_add_f32_e32 v21, 1.0, v21
	v_add_f32_e32 v22, 1.0, v22
	v_add_f32_e32 v23, 1.0, v23
	v_rcp_f32_e32 v25, v16
	v_add_f32_e32 v16, 1.0, v18
	v_mul_f32_e32 v9, v9, v145
	v_mul_f32_e32 v8, 0xbfb8aa3b, v8
	v_rcp_f32_e32 v20, v20
	v_rcp_f32_e32 v21, v21
	v_rcp_f32_e32 v22, v22
	v_rcp_f32_e32 v23, v23
	v_rcp_f32_e32 v26, v16
	v_exp_f32_e32 v8, v8
	v_mul_f32_e32 v9, 0xbfb8aa3b, v9
	v_exp_f32_e32 v9, v9
	v_lshl_add_u64 v[28:29], v[56:57], 0, s[14:15]
	v_cvt_pk_bf16_f32 v16, v20, v21
	v_cvt_pk_bf16_f32 v17, v22, v23
	v_cvt_pk_bf16_f32 v18, v24, v19
	v_cvt_pk_bf16_f32 v19, v25, v26
	v_mul_f32_e32 v14, v14, v145
	v_mul_f32_e32 v15, v15, v145
	v_mul_f32_e32 v10, v10, v145
	v_add_f32_e32 v8, 1.0, v8
	global_store_dwordx4 v[28:29], v[16:19], off offset:256
	v_mul_f32_e32 v12, v12, v145
	v_mul_f32_e32 v13, v13, v145
	v_mul_f32_e32 v11, v11, v145
	v_mul_f32_e32 v14, 0xbfb8aa3b, v14
	v_mul_f32_e32 v15, 0xbfb8aa3b, v15
	v_rcp_f32_e32 v16, v8
	v_add_f32_e32 v8, 1.0, v9
	v_mul_f32_e32 v9, 0xbfb8aa3b, v10
	v_mul_f32_e32 v12, 0xbfb8aa3b, v12
	v_mul_f32_e32 v13, 0xbfb8aa3b, v13
	v_exp_f32_e32 v14, v14
	v_exp_f32_e32 v15, v15
	v_exp_f32_e32 v9, v9
	v_mul_f32_e32 v10, 0xbfb8aa3b, v11
	v_exp_f32_e32 v12, v12
	v_exp_f32_e32 v13, v13
	v_exp_f32_e32 v10, v10
	v_add_f32_e32 v14, 1.0, v14
	v_add_f32_e32 v15, 1.0, v15
	v_rcp_f32_e32 v11, v8
	v_add_f32_e32 v8, 1.0, v9
	v_mul_f32_e32 v0, v0, v145
	v_add_f32_e32 v12, 1.0, v12
	v_add_f32_e32 v13, 1.0, v13
	v_rcp_f32_e32 v14, v14
	v_rcp_f32_e32 v15, v15
	v_rcp_f32_e32 v17, v8
	v_add_f32_e32 v8, 1.0, v10
	v_mul_f32_e32 v1, v1, v145
	v_mul_f32_e32 v0, 0xbfb8aa3b, v0
	v_rcp_f32_e32 v12, v12
	v_rcp_f32_e32 v13, v13
	v_rcp_f32_e32 v18, v8
	v_exp_f32_e32 v0, v0
	v_mul_f32_e32 v1, 0xbfb8aa3b, v1
	v_exp_f32_e32 v1, v1
	v_cvt_pk_bf16_f32 v9, v14, v15
	v_add_co_u32_e32 v14, vcc, s65, v56
	v_cvt_pk_bf16_f32 v8, v12, v13
	v_cvt_pk_bf16_f32 v10, v16, v11
	v_cvt_pk_bf16_f32 v11, v17, v18
	v_addc_co_u32_e32 v15, vcc, 0, v57, vcc
	v_mul_f32_e32 v2, v2, v145
	v_add_f32_e32 v0, 1.0, v0
	global_store_dwordx4 v[14:15], v[8:11], off
	v_mul_f32_e32 v4, v4, v145
	v_mul_f32_e32 v5, v5, v145
	v_mul_f32_e32 v6, v6, v145
	v_mul_f32_e32 v7, v7, v145
	v_mul_f32_e32 v3, v3, v145
	v_rcp_f32_e32 v8, v0
	v_add_f32_e32 v0, 1.0, v1
	v_mul_f32_e32 v1, 0xbfb8aa3b, v2
	v_mul_f32_e32 v4, 0xbfb8aa3b, v4
	v_mul_f32_e32 v5, 0xbfb8aa3b, v5
	v_mul_f32_e32 v6, 0xbfb8aa3b, v6
	v_mul_f32_e32 v7, 0xbfb8aa3b, v7
	v_exp_f32_e32 v1, v1
	v_mul_f32_e32 v2, 0xbfb8aa3b, v3
	v_exp_f32_e32 v4, v4
	v_exp_f32_e32 v5, v5
	v_exp_f32_e32 v6, v6
	v_exp_f32_e32 v7, v7
	v_exp_f32_e32 v2, v2
	v_rcp_f32_e32 v3, v0
	v_add_f32_e32 v0, 1.0, v1
	v_add_f32_e32 v4, 1.0, v4
	v_add_f32_e32 v5, 1.0, v5
	v_add_f32_e32 v6, 1.0, v6
	v_add_f32_e32 v7, 1.0, v7
	v_rcp_f32_e32 v9, v0
	v_add_f32_e32 v0, 1.0, v2
	v_rcp_f32_e32 v4, v4
	v_rcp_f32_e32 v5, v5
	v_rcp_f32_e32 v6, v6
	v_rcp_f32_e32 v7, v7
	v_rcp_f32_e32 v10, v0
	v_lshl_add_u64 v[12:13], v[56:57], 0, s[22:23]
	v_cvt_pk_bf16_f32 v0, v4, v5
	v_cvt_pk_bf16_f32 v1, v6, v7
	v_cvt_pk_bf16_f32 v2, v8, v3
	v_cvt_pk_bf16_f32 v3, v9, v10
	s_andn2_b64 vcc, exec, s[0:1]
	s_mov_b64 s[0:1], -1
	global_store_dwordx4 v[12:13], v[0:3], off offset:256
	s_waitcnt vmcnt(16)
	s_cbranch_vccnz .LBB0_1345
	s_andn2_b64 vcc, exec, s[6:7]
	s_cbranch_vccnz .LBB0_1344
	s_barrier
	s_branch .LBB0_1344
